# quadrant tail rounds for AB-in and LRU-in GEMMs: specialised K-loop copies drop unused half-tile loads/LDS reads, vmcnt(4)
# speedup vs baseline: 1.0733x; 1.0128x over previous
.LBB0_109:
	s_mul_i32 s66, s90, 0x2400
	s_add_u32 s34, s12, 0x10d00000
	s_addc_u32 s35, s13, 0
	s_lshl_b64 s[36:37], s[66:67], 2
	s_sext_i32_i8 s6, s2
	s_add_u32 s2, s12, s36
	v_lshrrev_b32_e32 v16, 1, v14
	s_addc_u32 s9, s13, s37
	v_and_b32_e32 v16, 24, v16
	s_add_u32 s38, s2, 0x7000
	v_and_b32_e32 v15, 15, v14
	v_lshlrev_b32_e32 v17, 1, v16
	v_lshlrev_b32_e32 v14, 2, v14
	s_addc_u32 s39, s9, 0
	v_lshl_or_b32 v146, s8, 6, v15
	v_lshl_or_b32 v15, v15, 6, v17
	s_lshl_b32 s2, s8, 13
	v_and_b32_e32 v14, 32, v14
	v_bitop3_b32 v17, v15, s2, v14 bitop3:0xde
	s_lshl_b32 s2, s7, 5
	s_and_b32 s2, s2, 0x60
	s_add_i32 m0, s5, 0x18000
	v_lshl_add_u64 v[6:7], v[6:7], 0, s[94:95]
	s_lshl_b32 s7, s2, 7
	s_waitcnt vmcnt(2)
	s_barrier
	global_load_lds_dwordx4 v[6:7], off
	v_lshl_add_u64 v[4:5], v[4:5], 0, s[94:95]
	s_add_i32 m0, s5, 0x1a000
	s_add_i32 s66, s5, 0x8000
	s_add_i32 s84, s5, 0xa000
	global_load_lds_dwordx4 v[4:5], off
	v_lshl_add_u64 v[0:1], v[0:1], 0, s[94:95]
	s_mov_b32 m0, s66
	s_add_u32 s8, s72, 0x80080
	global_load_lds_dwordx4 v[0:1], off
	v_lshl_add_u64 v[0:1], v[2:3], 0, s[94:95]
	s_mov_b32 m0, s84
	s_addc_u32 s9, s73, 0
	global_load_lds_dwordx4 v[0:1], off
	s_add_i32 m0, s5, 0x1c000
	v_lshl_add_u64 v[0:1], s[8:9], 0, v[144:145]
	global_load_lds_dwordx4 v[0:1], off
	v_lshl_add_u64 v[0:1], s[8:9], 0, v[128:129]
	s_add_i32 m0, s5, 0x1e000
	s_cmpk_lt_u32 s3, 0x100
	global_load_lds_dwordx4 v[0:1], off
	v_lshlrev_b32_e32 v0, 15, v8
	v_and_b32_e32 v0, 0xffff0000, v0
	v_lshl_add_u32 v0, v9, 12, v0
	v_and_b32_e32 v1, 1, v8
	v_lshl_or_b32 v0, v1, 6, v0
	v_lshl_add_u32 v134, v10, 1, v0
	v_lshlrev_b32_e32 v0, 15, v12
	v_and_b32_e32 v0, 0xffff0000, v0
	s_waitcnt vmcnt(6)
	v_lshl_add_u32 v0, v11, 12, v0
	v_and_b32_e32 v1, 1, v12
	v_lshl_or_b32 v0, v1, 6, v0
	v_bitop3_b32 v162, v15, s7, v14 bitop3:0xde
	s_cselect_b64 s[40:41], -1, 0
	v_or_b32_e32 v163, s2, v16
	v_mov_b32_e32 v135, v145
	v_lshl_add_u32 v136, v13, 1, v0
	v_mov_b32_e32 v137, v145
	s_mov_b32 s88, 0
	v_add_u32_e32 v164, 0, v17
	s_barrier
	s_mov_b32 s100, 15
	s_branch .LBB0_112

.LBB0_111:
	s_mov_b32 s100, s101
	s_andn2_b64 vcc, exec, s[2:3]
	s_mov_b32 s6, s52
	s_mov_b32 s4, s54
	s_mov_b64 s[72:73], s[82:83]
	s_mov_b64 s[74:75], s[68:69]
	s_cbranch_vccz .LBB0_121
.LBB0_112:
	s_add_i32 s88, s88, 1
	v_readlane_b32 s2, v246, 8
	s_mul_i32 s2, s88, s2
	s_mul_hi_u32 s3, s88, s48
	s_add_i32 s3, s3, s2
	s_mul_i32 s2, s88, s48
	s_add_u32 s2, s2, s22
	s_addc_u32 s3, s3, s62
	s_mov_b32 s101, 15
	s_cmp_eq_u32 s88, 2
	s_cbranch_scc0 .Lq_lin_sd
	s_lshr_b32 s101, s22, 6
	s_and_b32 s2, s22, 63
	s_add_u32 s2, s2, 0x200
	s_mov_b32 s3, 0
	s_lshl_b32 s101, 1, s101
.Lq_lin_sd:
	v_cmp_gt_i64_e32 vcc, s[2:3], v[150:151]
	v_cmp_lt_i64_e64 s[36:37], s[2:3], v[148:149]
	s_cbranch_vccnz .LBB0_114
	s_ashr_i32 s3, s2, 31
	s_lshr_b32 s3, s3, 29
	s_add_i32 s3, s2, s3
	s_ashr_i32 s7, s3, 3
	s_and_b32 s3, s3, -8
	s_sub_i32 s2, s2, s3
	s_cmp_lt_i32 s2, 0
	s_movk_i32 s3, 0x49
	s_cselect_b32 s3, s3, 0x48
	s_mul_i32 s2, s2, s3
	s_add_i32 s2, s2, s7
	s_ashr_i32 s3, s2, 31
	s_lshr_b32 s3, s3, 25
	s_add_i32 s3, s2, s3
	s_ashr_i32 s7, s3, 7
	s_lshl_b32 s7, s7, 3
	s_sub_i32 s8, 36, s7
	s_min_i32 s8, s8, 8
	s_abs_i32 s9, s8
	v_cvt_f32_u32_e32 v0, s9
	s_sub_i32 s25, 0, s9
	s_and_b32 s3, s3, 0xffffff80
	s_sub_i32 s2, s2, s3
	v_rcp_iflag_f32_e32 v0, v0
	s_abs_i32 s3, s2
	s_xor_b32 s24, s2, s8
	s_ashr_i32 s24, s24, 31
	v_mul_f32_e32 v0, 0x4f7ffffe, v0
	v_cvt_u32_f32_e32 v0, v0
	s_nop 0
	v_readfirstlane_b32 s52, v0
	s_mul_i32 s25, s25, s52
	s_mul_hi_u32 s25, s52, s25
	s_add_i32 s52, s52, s25
	s_mul_hi_u32 s25, s3, s52
	s_mul_i32 s52, s25, s9
	s_sub_i32 s3, s3, s52
	s_add_i32 s53, s25, 1
	s_sub_i32 s52, s3, s9
	s_cmp_ge_u32 s3, s9
	s_cselect_b32 s25, s53, s25
	s_cselect_b32 s3, s52, s3
	s_add_i32 s52, s25, 1
	s_cmp_ge_u32 s3, s9
	s_cselect_b32 s3, s52, s25
	s_xor_b32 s3, s3, s24
	s_sub_i32 s52, s3, s24
	s_mul_i32 s3, s52, s8
	s_sub_i32 s2, s2, s3
	s_add_i32 s54, s7, s2
.LBB0_114:
	s_ashr_i32 s55, s54, 31
	s_lshl_b64 s[2:3], s[54:55], 20
	s_add_u32 s68, s23, s2
	s_addc_u32 s69, s33, s3
	s_and_b64 s[2:3], s[36:37], exec
	s_cselect_b32 s7, s69, s75
	s_cselect_b32 s55, s68, s74
	s_ashr_i32 s53, s52, 31
	s_lshl_b64 s[2:3], s[52:53], 20
	s_add_u32 s82, s49, s2
	s_addc_u32 s83, s51, s3
	s_and_b64 s[2:3], s[36:37], exec
	s_cselect_b32 s53, s83, s73
	s_cselect_b32 s89, s82, s72
	s_add_u32 vcc_lo, s72, 0x100
	s_addc_u32 vcc_hi, s73, 0
	s_add_u32 s72, s74, 0x80080
	v_mov_b32_e32 v0, 0
	s_addc_u32 s73, s75, 0
	s_mov_b32 s8, -2
	v_mov_b32_e32 v1, v0
	v_mov_b32_e32 v2, v0
	v_mov_b32_e32 v3, v0
	v_mov_b32_e32 v4, v0
	v_mov_b32_e32 v5, v0
	v_mov_b32_e32 v6, v0
	v_mov_b32_e32 v7, v0
	v_mov_b32_e32 v16, v0
	v_mov_b32_e32 v17, v0
	v_mov_b32_e32 v18, v0
	v_mov_b32_e32 v19, v0
	v_mov_b32_e32 v20, v0
	v_mov_b32_e32 v21, v0
	v_mov_b32_e32 v22, v0
	v_mov_b32_e32 v23, v0
	v_mov_b32_e32 v32, v0
	v_mov_b32_e32 v33, v0
	v_mov_b32_e32 v34, v0
	v_mov_b32_e32 v35, v0
	v_mov_b32_e32 v36, v0
	v_mov_b32_e32 v37, v0
	v_mov_b32_e32 v38, v0
	v_mov_b32_e32 v39, v0
	v_mov_b32_e32 v48, v0
	v_mov_b32_e32 v49, v0
	v_mov_b32_e32 v50, v0
	v_mov_b32_e32 v51, v0
	v_mov_b32_e32 v52, v0
	v_mov_b32_e32 v53, v0
	v_mov_b32_e32 v54, v0
	v_mov_b32_e32 v55, v0
	v_mov_b32_e32 v8, v0
	v_mov_b32_e32 v9, v0
	v_mov_b32_e32 v10, v0
	v_mov_b32_e32 v11, v0
	v_mov_b32_e32 v12, v0
	v_mov_b32_e32 v13, v0
	v_mov_b32_e32 v14, v0
	v_mov_b32_e32 v15, v0
	v_mov_b32_e32 v24, v0
	v_mov_b32_e32 v25, v0
	v_mov_b32_e32 v26, v0
	v_mov_b32_e32 v27, v0
	v_mov_b32_e32 v28, v0
	v_mov_b32_e32 v29, v0
	v_mov_b32_e32 v30, v0
	v_mov_b32_e32 v31, v0
	v_mov_b32_e32 v40, v0
	v_mov_b32_e32 v41, v0
	v_mov_b32_e32 v42, v0
	v_mov_b32_e32 v43, v0
	v_mov_b32_e32 v44, v0
	v_mov_b32_e32 v45, v0
	v_mov_b32_e32 v46, v0
	v_mov_b32_e32 v47, v0
	v_mov_b32_e32 v56, v0
	v_mov_b32_e32 v57, v0
	v_mov_b32_e32 v58, v0
	v_mov_b32_e32 v59, v0
	v_mov_b32_e32 v60, v0
	v_mov_b32_e32 v61, v0
	v_mov_b32_e32 v62, v0
	v_mov_b32_e32 v63, v0
	v_mov_b32_e32 v64, v0
	v_mov_b32_e32 v65, v0
	v_mov_b32_e32 v66, v0
	v_mov_b32_e32 v67, v0
	v_mov_b32_e32 v68, v0
	v_mov_b32_e32 v69, v0
	v_mov_b32_e32 v70, v0
	v_mov_b32_e32 v71, v0
	v_mov_b32_e32 v80, v0
	v_mov_b32_e32 v81, v0
	v_mov_b32_e32 v82, v0
	v_mov_b32_e32 v83, v0
	v_mov_b32_e32 v84, v0
	v_mov_b32_e32 v85, v0
	v_mov_b32_e32 v86, v0
	v_mov_b32_e32 v87, v0
	v_mov_b32_e32 v96, v0
	v_mov_b32_e32 v97, v0
	v_mov_b32_e32 v98, v0
	v_mov_b32_e32 v99, v0
	v_mov_b32_e32 v100, v0
	v_mov_b32_e32 v101, v0
	v_mov_b32_e32 v102, v0
	v_mov_b32_e32 v103, v0
	v_mov_b32_e32 v112, v0
	v_mov_b32_e32 v113, v0
	v_mov_b32_e32 v114, v0
	v_mov_b32_e32 v115, v0
	v_mov_b32_e32 v116, v0
	v_mov_b32_e32 v117, v0
	v_mov_b32_e32 v118, v0
	v_mov_b32_e32 v119, v0
	v_mov_b32_e32 v72, v0
	v_mov_b32_e32 v73, v0
	v_mov_b32_e32 v74, v0
	v_mov_b32_e32 v75, v0
	v_mov_b32_e32 v76, v0
	v_mov_b32_e32 v77, v0
	v_mov_b32_e32 v78, v0
	v_mov_b32_e32 v79, v0
	v_mov_b32_e32 v88, v0
	v_mov_b32_e32 v89, v0
	v_mov_b32_e32 v90, v0
	v_mov_b32_e32 v91, v0
	v_mov_b32_e32 v92, v0
	v_mov_b32_e32 v93, v0
	v_mov_b32_e32 v94, v0
	v_mov_b32_e32 v95, v0
	v_mov_b32_e32 v104, v0
	v_mov_b32_e32 v105, v0
	v_mov_b32_e32 v106, v0
	v_mov_b32_e32 v107, v0
	v_mov_b32_e32 v108, v0
	v_mov_b32_e32 v109, v0
	v_mov_b32_e32 v110, v0
	v_mov_b32_e32 v111, v0
	v_mov_b32_e32 v120, v0
	v_mov_b32_e32 v121, v0
	v_mov_b32_e32 v122, v0
	v_mov_b32_e32 v123, v0
	v_mov_b32_e32 v124, v0
	v_mov_b32_e32 v125, v0
	v_mov_b32_e32 v126, v0
	v_mov_b32_e32 v127, v0
	s_cmp_eq_u32 s100, 15
	s_cbranch_scc0 .Lq_lin_disp
.LBB0_115:
	s_add_u32 s2, s72, 0xfff80080
	s_addc_u32 s3, s73, -1
	s_add_i32 s9, 0, 0x10000
	s_cmp_eq_u32 s8, 28
	s_cselect_b32 s75, s7, s3
	s_cselect_b32 s74, s55, s2
	v_add_u32_e32 v142, s9, v162
	s_cselect_b32 s3, s53, vcc_hi
	s_cselect_b32 s2, s89, vcc_lo
	s_add_i32 s26, 0, 0x14000
	ds_read_b128 v[138:141], v142
	ds_read_b128 v[166:169], v142 offset:1024
	ds_read_b128 v[170:173], v142 offset:2048
	ds_read_b128 v[174:177], v142 offset:3072
	v_add_u32_e32 v142, s26, v162
	ds_read_b128 v[190:193], v142
	ds_read_b128 v[194:197], v142 offset:1024
	ds_read_b128 v[198:201], v142 offset:2048
	ds_read_b128 v[202:205], v142 offset:3072
	v_lshl_add_u64 v[142:143], s[72:73], 0, v[136:137]
	s_add_i32 m0, s5, 0xc000
	ds_read_b128 v[206:209], v164
	ds_read_b128 v[210:213], v164 offset:1024
	ds_read_b128 v[214:217], v164 offset:2048
	ds_read_b128 v[218:221], v164 offset:3072
	ds_read_b128 v[222:225], v164 offset:4096
	ds_read_b128 v[226:229], v164 offset:5120
	ds_read_b128 v[230:233], v164 offset:6144
	ds_read_b128 v[234:237], v164 offset:7168
	global_load_lds_dwordx4 v[142:143], off
	v_lshl_add_u64 v[142:143], s[72:73], 0, v[134:135]
	s_add_i32 m0, s5, 0xe000
	s_nop 0
	global_load_lds_dwordx4 v[142:143], off
	s_waitcnt vmcnt(8)
	s_waitcnt lgkmcnt(0)
	s_barrier
	s_setprio 1
	s_waitcnt lgkmcnt(0)
	v_mfma_f32_16x16x32_bf16 v[124:127], v[138:141], v[206:209], v[124:127]
	v_mfma_f32_16x16x32_bf16 v[120:123], v[170:173], v[206:209], v[120:123]
	v_mfma_f32_16x16x32_bf16 v[108:111], v[138:141], v[214:217], v[108:111]
	v_mfma_f32_16x16x32_bf16 v[104:107], v[170:173], v[214:217], v[104:107]
	v_mfma_f32_16x16x32_bf16 v[92:95], v[138:141], v[222:225], v[92:95]
	v_mfma_f32_16x16x32_bf16 v[88:91], v[170:173], v[222:225], v[88:91]
	v_mfma_f32_16x16x32_bf16 v[76:79], v[138:141], v[230:233], v[76:79]
	v_mfma_f32_16x16x32_bf16 v[72:75], v[170:173], v[230:233], v[72:75]
	v_mfma_f32_16x16x32_bf16 v[124:127], v[166:169], v[210:213], v[124:127]
	v_mfma_f32_16x16x32_bf16 v[120:123], v[174:177], v[210:213], v[120:123]
	v_mfma_f32_16x16x32_bf16 v[108:111], v[166:169], v[218:221], v[108:111]
	v_mfma_f32_16x16x32_bf16 v[104:107], v[174:177], v[218:221], v[104:107]
	v_mfma_f32_16x16x32_bf16 v[92:95], v[166:169], v[226:229], v[92:95]
	v_mfma_f32_16x16x32_bf16 v[88:91], v[174:177], v[226:229], v[88:91]
	v_mfma_f32_16x16x32_bf16 v[76:79], v[166:169], v[234:237], v[76:79]
	v_mfma_f32_16x16x32_bf16 v[72:75], v[174:177], v[234:237], v[72:75]
	s_setprio 0
	s_setprio 1
	v_mfma_f32_16x16x32_bf16 v[116:119], v[190:193], v[206:209], v[116:119]
	v_mfma_f32_16x16x32_bf16 v[112:115], v[198:201], v[206:209], v[112:115]
	v_mfma_f32_16x16x32_bf16 v[100:103], v[190:193], v[214:217], v[100:103]
	v_mfma_f32_16x16x32_bf16 v[96:99], v[198:201], v[214:217], v[96:99]
	v_mfma_f32_16x16x32_bf16 v[84:87], v[190:193], v[222:225], v[84:87]
	v_mfma_f32_16x16x32_bf16 v[80:83], v[198:201], v[222:225], v[80:83]
	v_mfma_f32_16x16x32_bf16 v[68:71], v[190:193], v[230:233], v[68:71]
	v_mfma_f32_16x16x32_bf16 v[64:67], v[198:201], v[230:233], v[64:67]
	v_mfma_f32_16x16x32_bf16 v[116:119], v[194:197], v[210:213], v[116:119]
	v_mfma_f32_16x16x32_bf16 v[112:115], v[202:205], v[210:213], v[112:115]
	v_mfma_f32_16x16x32_bf16 v[100:103], v[194:197], v[218:221], v[100:103]
	v_mfma_f32_16x16x32_bf16 v[96:99], v[202:205], v[218:221], v[96:99]
	v_mfma_f32_16x16x32_bf16 v[84:87], v[194:197], v[226:229], v[84:87]
	v_mfma_f32_16x16x32_bf16 v[80:83], v[202:205], v[226:229], v[80:83]
	v_mfma_f32_16x16x32_bf16 v[68:71], v[194:197], v[234:237], v[68:71]
	v_mfma_f32_16x16x32_bf16 v[64:67], v[202:205], v[234:237], v[64:67]
	s_setprio 0
	s_barrier
	s_add_i32 s9, s9, s61
	v_lshl_add_u64 v[142:143], s[2:3], 0, v[144:145]
	s_mov_b32 m0, s9
	ds_read_b128 v[206:209], v164 offset:16384
	ds_read_b128 v[210:213], v164 offset:17408
	ds_read_b128 v[214:217], v164 offset:18432
	ds_read_b128 v[218:221], v164 offset:19456
	ds_read_b128 v[222:225], v164 offset:20480
	ds_read_b128 v[226:229], v164 offset:21504
	ds_read_b128 v[230:233], v164 offset:22528
	ds_read_b128 v[234:237], v164 offset:23552
	global_load_lds_dwordx4 v[142:143], off
	s_add_i32 m0, s9, 0x2000
	s_add_u32 s24, s2, 0x80000
	v_lshl_add_u64 v[160:161], s[2:3], 0, v[128:129]
	s_addc_u32 s25, s3, 0
	s_add_i32 s9, s26, s61
	global_load_lds_dwordx4 v[160:161], off
	v_lshl_add_u64 v[178:179], s[24:25], 0, v[144:145]
	s_mov_b32 m0, s9
	v_lshl_add_u64 v[238:239], s[74:75], 0, v[130:131]
	global_load_lds_dwordx4 v[178:179], off
	v_lshl_add_u64 v[178:179], s[24:25], 0, v[128:129]
	s_add_i32 m0, s9, 0x2000
	s_nop 0
	global_load_lds_dwordx4 v[178:179], off
	v_lshl_add_u64 v[178:179], s[74:75], 0, v[132:133]
	s_mov_b32 m0, s5
	s_nop 0
	global_load_lds_dwordx4 v[178:179], off
	s_mov_b32 m0, s63
	s_nop 0
	global_load_lds_dwordx4 v[238:239], off
	s_waitcnt vmcnt(8)
	s_waitcnt lgkmcnt(0)
	s_barrier
	s_setprio 1
	s_waitcnt lgkmcnt(0)
	v_mfma_f32_16x16x32_bf16 v[60:63], v[138:141], v[206:209], v[60:63]
	v_mfma_f32_16x16x32_bf16 v[56:59], v[170:173], v[206:209], v[56:59]
	v_mfma_f32_16x16x32_bf16 v[44:47], v[138:141], v[214:217], v[44:47]
	v_mfma_f32_16x16x32_bf16 v[40:43], v[170:173], v[214:217], v[40:43]
	v_mfma_f32_16x16x32_bf16 v[28:31], v[138:141], v[222:225], v[28:31]
	v_mfma_f32_16x16x32_bf16 v[24:27], v[170:173], v[222:225], v[24:27]
	v_mfma_f32_16x16x32_bf16 v[12:15], v[138:141], v[230:233], v[12:15]
	v_mfma_f32_16x16x32_bf16 v[8:11], v[170:173], v[230:233], v[8:11]
	v_mfma_f32_16x16x32_bf16 v[60:63], v[166:169], v[210:213], v[60:63]
	v_mfma_f32_16x16x32_bf16 v[56:59], v[174:177], v[210:213], v[56:59]
	v_mfma_f32_16x16x32_bf16 v[44:47], v[166:169], v[218:221], v[44:47]
	v_mfma_f32_16x16x32_bf16 v[40:43], v[174:177], v[218:221], v[40:43]
	v_mfma_f32_16x16x32_bf16 v[28:31], v[166:169], v[226:229], v[28:31]
	v_mfma_f32_16x16x32_bf16 v[24:27], v[174:177], v[226:229], v[24:27]
	v_mfma_f32_16x16x32_bf16 v[12:15], v[166:169], v[234:237], v[12:15]
	v_mfma_f32_16x16x32_bf16 v[8:11], v[174:177], v[234:237], v[8:11]
	s_setprio 0
	s_setprio 1
	v_mfma_f32_16x16x32_bf16 v[52:55], v[190:193], v[206:209], v[52:55]
	v_mfma_f32_16x16x32_bf16 v[48:51], v[198:201], v[206:209], v[48:51]
	v_mfma_f32_16x16x32_bf16 v[36:39], v[190:193], v[214:217], v[36:39]
	v_mfma_f32_16x16x32_bf16 v[32:35], v[198:201], v[214:217], v[32:35]
	v_mfma_f32_16x16x32_bf16 v[20:23], v[190:193], v[222:225], v[20:23]
	v_mfma_f32_16x16x32_bf16 v[16:19], v[198:201], v[222:225], v[16:19]
	v_mfma_f32_16x16x32_bf16 v[4:7], v[190:193], v[230:233], v[4:7]
	v_mfma_f32_16x16x32_bf16 v[0:3], v[198:201], v[230:233], v[0:3]
	v_mfma_f32_16x16x32_bf16 v[52:55], v[194:197], v[210:213], v[52:55]
	v_mfma_f32_16x16x32_bf16 v[48:51], v[202:205], v[210:213], v[48:51]
	v_mfma_f32_16x16x32_bf16 v[36:39], v[194:197], v[218:221], v[36:39]
	v_mfma_f32_16x16x32_bf16 v[32:35], v[202:205], v[218:221], v[32:35]
	v_mfma_f32_16x16x32_bf16 v[20:23], v[194:197], v[226:229], v[20:23]
	v_mfma_f32_16x16x32_bf16 v[16:19], v[202:205], v[226:229], v[16:19]
	v_mfma_f32_16x16x32_bf16 v[4:7], v[194:197], v[234:237], v[4:7]
	v_mfma_f32_16x16x32_bf16 v[0:3], v[202:205], v[234:237], v[0:3]
	s_setprio 0
	s_barrier
	s_add_i32 s9, 0, 0x18000
	v_add_u32_e32 v165, s9, v162
	s_add_i32 s26, 0, 0x1c000
	ds_read_b128 v[138:141], v165
	ds_read_b128 v[166:169], v165 offset:1024
	ds_read_b128 v[170:173], v165 offset:2048
	ds_read_b128 v[174:177], v165 offset:3072
	v_add_u32_e32 v165, s26, v162
	ds_read_b128 v[190:193], v165
	ds_read_b128 v[194:197], v165 offset:1024
	ds_read_b128 v[198:201], v165 offset:2048
	ds_read_b128 v[202:205], v165 offset:3072
	s_add_u32 s24, s74, 0x80000
	s_addc_u32 s25, s75, 0
	s_mov_b32 m0, s64
	v_lshl_add_u64 v[240:241], s[24:25], 0, v[132:133]
	ds_read_b128 v[206:209], v164 offset:32768
	ds_read_b128 v[210:213], v164 offset:33792
	ds_read_b128 v[214:217], v164 offset:34816
	ds_read_b128 v[218:221], v164 offset:35840
	ds_read_b128 v[222:225], v164 offset:36864
	ds_read_b128 v[226:229], v164 offset:37888
	ds_read_b128 v[230:233], v164 offset:38912
	ds_read_b128 v[234:237], v164 offset:39936
	global_load_lds_dwordx4 v[240:241], off
	v_lshl_add_u64 v[240:241], s[24:25], 0, v[130:131]
	s_mov_b32 m0, s65
	s_nop 0
	global_load_lds_dwordx4 v[240:241], off
	s_waitcnt vmcnt(8)
	s_waitcnt lgkmcnt(0)
	s_barrier
	s_setprio 1
	s_waitcnt lgkmcnt(0)
	v_mfma_f32_16x16x32_bf16 v[124:127], v[138:141], v[206:209], v[124:127]
	v_mfma_f32_16x16x32_bf16 v[120:123], v[170:173], v[206:209], v[120:123]
	v_mfma_f32_16x16x32_bf16 v[108:111], v[138:141], v[214:217], v[108:111]
	v_mfma_f32_16x16x32_bf16 v[104:107], v[170:173], v[214:217], v[104:107]
	v_mfma_f32_16x16x32_bf16 v[92:95], v[138:141], v[222:225], v[92:95]
	v_mfma_f32_16x16x32_bf16 v[88:91], v[170:173], v[222:225], v[88:91]
	v_mfma_f32_16x16x32_bf16 v[76:79], v[138:141], v[230:233], v[76:79]
	v_mfma_f32_16x16x32_bf16 v[72:75], v[170:173], v[230:233], v[72:75]
	v_mfma_f32_16x16x32_bf16 v[124:127], v[166:169], v[210:213], v[124:127]
	v_mfma_f32_16x16x32_bf16 v[120:123], v[174:177], v[210:213], v[120:123]
	v_mfma_f32_16x16x32_bf16 v[108:111], v[166:169], v[218:221], v[108:111]
	v_mfma_f32_16x16x32_bf16 v[104:107], v[174:177], v[218:221], v[104:107]
	v_mfma_f32_16x16x32_bf16 v[92:95], v[166:169], v[226:229], v[92:95]
	v_mfma_f32_16x16x32_bf16 v[88:91], v[174:177], v[226:229], v[88:91]
	v_mfma_f32_16x16x32_bf16 v[76:79], v[166:169], v[234:237], v[76:79]
	v_mfma_f32_16x16x32_bf16 v[72:75], v[174:177], v[234:237], v[72:75]
	s_setprio 0
	s_setprio 1
	v_mfma_f32_16x16x32_bf16 v[116:119], v[190:193], v[206:209], v[116:119]
	v_mfma_f32_16x16x32_bf16 v[112:115], v[198:201], v[206:209], v[112:115]
	v_mfma_f32_16x16x32_bf16 v[100:103], v[190:193], v[214:217], v[100:103]
	v_mfma_f32_16x16x32_bf16 v[96:99], v[198:201], v[214:217], v[96:99]
	v_mfma_f32_16x16x32_bf16 v[84:87], v[190:193], v[222:225], v[84:87]
	v_mfma_f32_16x16x32_bf16 v[80:83], v[198:201], v[222:225], v[80:83]
	v_mfma_f32_16x16x32_bf16 v[68:71], v[190:193], v[230:233], v[68:71]
	v_mfma_f32_16x16x32_bf16 v[64:67], v[198:201], v[230:233], v[64:67]
	v_mfma_f32_16x16x32_bf16 v[116:119], v[194:197], v[210:213], v[116:119]
	v_mfma_f32_16x16x32_bf16 v[112:115], v[202:205], v[210:213], v[112:115]
	v_mfma_f32_16x16x32_bf16 v[100:103], v[194:197], v[218:221], v[100:103]
	v_mfma_f32_16x16x32_bf16 v[96:99], v[202:205], v[218:221], v[96:99]
	v_mfma_f32_16x16x32_bf16 v[84:87], v[194:197], v[226:229], v[84:87]
	v_mfma_f32_16x16x32_bf16 v[80:83], v[202:205], v[226:229], v[80:83]
	v_mfma_f32_16x16x32_bf16 v[68:71], v[194:197], v[234:237], v[68:71]
	v_mfma_f32_16x16x32_bf16 v[64:67], v[202:205], v[234:237], v[64:67]
	s_setprio 0
	s_barrier
	s_add_i32 s9, s9, s61
	v_lshl_add_u64 v[142:143], v[142:143], 0, s[94:95]
	s_mov_b32 m0, s9
	ds_read_b128 v[206:209], v164 offset:49152
	ds_read_b128 v[210:213], v164 offset:50176
	ds_read_b128 v[214:217], v164 offset:51200
	ds_read_b128 v[218:221], v164 offset:52224
	ds_read_b128 v[222:225], v164 offset:53248
	ds_read_b128 v[226:229], v164 offset:54272
	ds_read_b128 v[230:233], v164 offset:55296
	ds_read_b128 v[234:237], v164 offset:56320
	global_load_lds_dwordx4 v[142:143], off
	s_add_i32 m0, s9, 0x2000
	s_add_u32 s2, s2, 0x80080
	v_lshl_add_u64 v[142:143], v[160:161], 0, s[94:95]
	s_addc_u32 s3, s3, 0
	s_add_i32 s9, s26, s61
	global_load_lds_dwordx4 v[142:143], off
	v_lshl_add_u64 v[142:143], s[2:3], 0, v[144:145]
	s_mov_b32 m0, s9
	s_nop 0
	global_load_lds_dwordx4 v[142:143], off
	v_lshl_add_u64 v[142:143], s[2:3], 0, v[128:129]
	s_add_i32 m0, s9, 0x2000
	s_nop 0
	global_load_lds_dwordx4 v[142:143], off
	v_lshl_add_u64 v[142:143], v[178:179], 0, s[94:95]
	s_mov_b32 m0, s66
	s_nop 0
	global_load_lds_dwordx4 v[142:143], off
	v_lshl_add_u64 v[142:143], v[238:239], 0, s[94:95]
	s_mov_b32 m0, s84
	s_nop 0
	global_load_lds_dwordx4 v[142:143], off
	s_waitcnt vmcnt(8)
	s_waitcnt lgkmcnt(0)
	s_barrier
	s_setprio 1
	s_waitcnt lgkmcnt(0)
	v_mfma_f32_16x16x32_bf16 v[60:63], v[138:141], v[206:209], v[60:63]
	v_mfma_f32_16x16x32_bf16 v[56:59], v[170:173], v[206:209], v[56:59]
	v_mfma_f32_16x16x32_bf16 v[44:47], v[138:141], v[214:217], v[44:47]
	v_mfma_f32_16x16x32_bf16 v[40:43], v[170:173], v[214:217], v[40:43]
	v_mfma_f32_16x16x32_bf16 v[28:31], v[138:141], v[222:225], v[28:31]
	v_mfma_f32_16x16x32_bf16 v[24:27], v[170:173], v[222:225], v[24:27]
	v_mfma_f32_16x16x32_bf16 v[12:15], v[138:141], v[230:233], v[12:15]
	v_mfma_f32_16x16x32_bf16 v[8:11], v[170:173], v[230:233], v[8:11]
	v_mfma_f32_16x16x32_bf16 v[60:63], v[166:169], v[210:213], v[60:63]
	v_mfma_f32_16x16x32_bf16 v[56:59], v[174:177], v[210:213], v[56:59]
	v_mfma_f32_16x16x32_bf16 v[44:47], v[166:169], v[218:221], v[44:47]
	v_mfma_f32_16x16x32_bf16 v[40:43], v[174:177], v[218:221], v[40:43]
	v_mfma_f32_16x16x32_bf16 v[28:31], v[166:169], v[226:229], v[28:31]
	v_mfma_f32_16x16x32_bf16 v[24:27], v[174:177], v[226:229], v[24:27]
	v_mfma_f32_16x16x32_bf16 v[12:15], v[166:169], v[234:237], v[12:15]
	v_mfma_f32_16x16x32_bf16 v[8:11], v[174:177], v[234:237], v[8:11]
	s_setprio 0
	s_setprio 1
	v_mfma_f32_16x16x32_bf16 v[52:55], v[190:193], v[206:209], v[52:55]
	v_mfma_f32_16x16x32_bf16 v[48:51], v[198:201], v[206:209], v[48:51]
	v_mfma_f32_16x16x32_bf16 v[36:39], v[190:193], v[214:217], v[36:39]
	v_mfma_f32_16x16x32_bf16 v[32:35], v[198:201], v[214:217], v[32:35]
	v_mfma_f32_16x16x32_bf16 v[20:23], v[190:193], v[222:225], v[20:23]
	v_mfma_f32_16x16x32_bf16 v[16:19], v[198:201], v[222:225], v[16:19]
	v_mfma_f32_16x16x32_bf16 v[4:7], v[190:193], v[230:233], v[4:7]
	v_mfma_f32_16x16x32_bf16 v[0:3], v[198:201], v[230:233], v[0:3]
	v_mfma_f32_16x16x32_bf16 v[52:55], v[194:197], v[210:213], v[52:55]
	v_mfma_f32_16x16x32_bf16 v[48:51], v[202:205], v[210:213], v[48:51]
	v_mfma_f32_16x16x32_bf16 v[36:39], v[194:197], v[218:221], v[36:39]
	v_mfma_f32_16x16x32_bf16 v[32:35], v[202:205], v[218:221], v[32:35]
	v_mfma_f32_16x16x32_bf16 v[20:23], v[194:197], v[226:229], v[20:23]
	v_mfma_f32_16x16x32_bf16 v[16:19], v[202:205], v[226:229], v[16:19]
	v_mfma_f32_16x16x32_bf16 v[4:7], v[194:197], v[234:237], v[4:7]
	v_mfma_f32_16x16x32_bf16 v[0:3], v[202:205], v[234:237], v[0:3]
	s_setprio 0
	s_barrier
	s_add_i32 s8, s8, 2
	s_add_u32 vcc_lo, vcc_lo, 0x100
	s_addc_u32 vcc_hi, vcc_hi, 0
	s_add_u32 s72, s72, 0x100
	s_addc_u32 s73, s73, 0
	s_cmp_gt_u32 s8, 29
	s_cbranch_scc0 .LBB0_115
	s_branch .Lq_lin_exit
.Lq_lin_disp:
	s_cmp_eq_u32 s100, 1
	s_cbranch_scc1 .Lq_lin_0_loop
	s_cmp_eq_u32 s100, 2
	s_cbranch_scc1 .Lq_lin_1_loop
	s_cmp_eq_u32 s100, 4
	s_cbranch_scc1 .Lq_lin_2_loop
	s_branch .Lq_lin_3_loop
.Lq_lin_0_loop:
	s_add_u32 s2, s72, 0xfff80080
	s_addc_u32 s3, s73, -1
	s_add_i32 s9, 0, 0x10000
	s_cmp_eq_u32 s8, 28
	s_cselect_b32 s75, s7, s3
	s_cselect_b32 s74, s55, s2
	v_add_u32_e32 v142, s9, v162
	s_cselect_b32 s3, s53, vcc_hi
	s_cselect_b32 s2, s89, vcc_lo
	s_add_i32 s26, 0, 0x14000
	ds_read_b128 v[138:141], v142
	ds_read_b128 v[166:169], v142 offset:1024
	ds_read_b128 v[170:173], v142 offset:2048
	ds_read_b128 v[174:177], v142 offset:3072
	v_add_u32_e32 v142, s26, v162
	v_lshl_add_u64 v[142:143], s[72:73], 0, v[136:137]
	s_add_i32 m0, s5, 0xc000
	ds_read_b128 v[206:209], v164
	ds_read_b128 v[210:213], v164 offset:1024
	ds_read_b128 v[214:217], v164 offset:2048
	ds_read_b128 v[218:221], v164 offset:3072
	ds_read_b128 v[222:225], v164 offset:4096
	ds_read_b128 v[226:229], v164 offset:5120
	ds_read_b128 v[230:233], v164 offset:6144
	ds_read_b128 v[234:237], v164 offset:7168
	v_lshl_add_u64 v[142:143], s[72:73], 0, v[134:135]
	s_add_i32 m0, s5, 0xe000
	s_nop 0
	s_waitcnt vmcnt(4)
	s_waitcnt lgkmcnt(0)
	s_barrier
	s_setprio 1
	s_waitcnt lgkmcnt(0)
	v_mfma_f32_16x16x32_bf16 v[124:127], v[138:141], v[206:209], v[124:127]
	v_mfma_f32_16x16x32_bf16 v[120:123], v[170:173], v[206:209], v[120:123]
	v_mfma_f32_16x16x32_bf16 v[108:111], v[138:141], v[214:217], v[108:111]
	v_mfma_f32_16x16x32_bf16 v[104:107], v[170:173], v[214:217], v[104:107]
	v_mfma_f32_16x16x32_bf16 v[92:95], v[138:141], v[222:225], v[92:95]
	v_mfma_f32_16x16x32_bf16 v[88:91], v[170:173], v[222:225], v[88:91]
	v_mfma_f32_16x16x32_bf16 v[76:79], v[138:141], v[230:233], v[76:79]
	v_mfma_f32_16x16x32_bf16 v[72:75], v[170:173], v[230:233], v[72:75]
	v_mfma_f32_16x16x32_bf16 v[124:127], v[166:169], v[210:213], v[124:127]
	v_mfma_f32_16x16x32_bf16 v[120:123], v[174:177], v[210:213], v[120:123]
	v_mfma_f32_16x16x32_bf16 v[108:111], v[166:169], v[218:221], v[108:111]
	v_mfma_f32_16x16x32_bf16 v[104:107], v[174:177], v[218:221], v[104:107]
	v_mfma_f32_16x16x32_bf16 v[92:95], v[166:169], v[226:229], v[92:95]
	v_mfma_f32_16x16x32_bf16 v[88:91], v[174:177], v[226:229], v[88:91]
	v_mfma_f32_16x16x32_bf16 v[76:79], v[166:169], v[234:237], v[76:79]
	v_mfma_f32_16x16x32_bf16 v[72:75], v[174:177], v[234:237], v[72:75]
	s_setprio 0
	s_setprio 1
	s_setprio 0
	s_barrier
	s_add_i32 s9, s9, s61
	v_lshl_add_u64 v[142:143], s[2:3], 0, v[144:145]
	s_mov_b32 m0, s9
	s_nop 0
	global_load_lds_dwordx4 v[142:143], off
	s_add_i32 m0, s9, 0x2000
	s_add_u32 s24, s2, 0x80000
	v_lshl_add_u64 v[160:161], s[2:3], 0, v[128:129]
	s_addc_u32 s25, s3, 0
	s_add_i32 s9, s26, s61
	global_load_lds_dwordx4 v[160:161], off
	v_lshl_add_u64 v[178:179], s[24:25], 0, v[144:145]
	s_mov_b32 m0, s9
	v_lshl_add_u64 v[238:239], s[74:75], 0, v[130:131]
	v_lshl_add_u64 v[178:179], s[24:25], 0, v[128:129]
	s_add_i32 m0, s9, 0x2000
	s_nop 0
	v_lshl_add_u64 v[178:179], s[74:75], 0, v[132:133]
	s_mov_b32 m0, s5
	s_nop 0
	global_load_lds_dwordx4 v[178:179], off
	s_mov_b32 m0, s63
	s_nop 0
	global_load_lds_dwordx4 v[238:239], off
	s_waitcnt vmcnt(4)
	s_waitcnt lgkmcnt(0)
	s_barrier
	s_setprio 1
	s_waitcnt lgkmcnt(0)
	s_setprio 0
	s_setprio 1
	s_setprio 0
	s_barrier
	s_add_i32 s9, 0, 0x18000
	v_add_u32_e32 v165, s9, v162
	s_add_i32 s26, 0, 0x1c000
	ds_read_b128 v[138:141], v165
	ds_read_b128 v[166:169], v165 offset:1024
	ds_read_b128 v[170:173], v165 offset:2048
	ds_read_b128 v[174:177], v165 offset:3072
	v_add_u32_e32 v165, s26, v162
	s_add_u32 s24, s74, 0x80000
	s_addc_u32 s25, s75, 0
	s_mov_b32 m0, s64
	v_lshl_add_u64 v[240:241], s[24:25], 0, v[132:133]
	ds_read_b128 v[206:209], v164 offset:32768
	ds_read_b128 v[210:213], v164 offset:33792
	ds_read_b128 v[214:217], v164 offset:34816
	ds_read_b128 v[218:221], v164 offset:35840
	ds_read_b128 v[222:225], v164 offset:36864
	ds_read_b128 v[226:229], v164 offset:37888
	ds_read_b128 v[230:233], v164 offset:38912
	ds_read_b128 v[234:237], v164 offset:39936
	v_lshl_add_u64 v[240:241], s[24:25], 0, v[130:131]
	s_mov_b32 m0, s65
	s_nop 0
	s_waitcnt vmcnt(4)
	s_waitcnt lgkmcnt(0)
	s_barrier
	s_setprio 1
	s_waitcnt lgkmcnt(0)
	v_mfma_f32_16x16x32_bf16 v[124:127], v[138:141], v[206:209], v[124:127]
	v_mfma_f32_16x16x32_bf16 v[120:123], v[170:173], v[206:209], v[120:123]
	v_mfma_f32_16x16x32_bf16 v[108:111], v[138:141], v[214:217], v[108:111]
	v_mfma_f32_16x16x32_bf16 v[104:107], v[170:173], v[214:217], v[104:107]
	v_mfma_f32_16x16x32_bf16 v[92:95], v[138:141], v[222:225], v[92:95]
	v_mfma_f32_16x16x32_bf16 v[88:91], v[170:173], v[222:225], v[88:91]
	v_mfma_f32_16x16x32_bf16 v[76:79], v[138:141], v[230:233], v[76:79]
	v_mfma_f32_16x16x32_bf16 v[72:75], v[170:173], v[230:233], v[72:75]
	v_mfma_f32_16x16x32_bf16 v[124:127], v[166:169], v[210:213], v[124:127]
	v_mfma_f32_16x16x32_bf16 v[120:123], v[174:177], v[210:213], v[120:123]
	v_mfma_f32_16x16x32_bf16 v[108:111], v[166:169], v[218:221], v[108:111]
	v_mfma_f32_16x16x32_bf16 v[104:107], v[174:177], v[218:221], v[104:107]
	v_mfma_f32_16x16x32_bf16 v[92:95], v[166:169], v[226:229], v[92:95]
	v_mfma_f32_16x16x32_bf16 v[88:91], v[174:177], v[226:229], v[88:91]
	v_mfma_f32_16x16x32_bf16 v[76:79], v[166:169], v[234:237], v[76:79]
	v_mfma_f32_16x16x32_bf16 v[72:75], v[174:177], v[234:237], v[72:75]
	s_setprio 0
	s_setprio 1
	s_setprio 0
	s_barrier
	s_add_i32 s9, s9, s61
	v_lshl_add_u64 v[142:143], v[142:143], 0, s[94:95]
	s_mov_b32 m0, s9
	s_nop 0
	global_load_lds_dwordx4 v[142:143], off
	s_add_i32 m0, s9, 0x2000
	s_add_u32 s2, s2, 0x80080
	v_lshl_add_u64 v[142:143], v[160:161], 0, s[94:95]
	s_addc_u32 s3, s3, 0
	s_add_i32 s9, s26, s61
	global_load_lds_dwordx4 v[142:143], off
	v_lshl_add_u64 v[142:143], s[2:3], 0, v[144:145]
	s_mov_b32 m0, s9
	s_nop 0
	v_lshl_add_u64 v[142:143], s[2:3], 0, v[128:129]
	s_add_i32 m0, s9, 0x2000
	s_nop 0
	v_lshl_add_u64 v[142:143], v[178:179], 0, s[94:95]
	s_mov_b32 m0, s66
	s_nop 0
	global_load_lds_dwordx4 v[142:143], off
	v_lshl_add_u64 v[142:143], v[238:239], 0, s[94:95]
	s_mov_b32 m0, s84
	s_nop 0
	global_load_lds_dwordx4 v[142:143], off
	s_waitcnt vmcnt(4)
	s_waitcnt lgkmcnt(0)
	s_barrier
	s_setprio 1
	s_waitcnt lgkmcnt(0)
	s_setprio 0
	s_setprio 1
	s_setprio 0
	s_barrier
	s_add_i32 s8, s8, 2
	s_add_u32 vcc_lo, vcc_lo, 0x100
	s_addc_u32 vcc_hi, vcc_hi, 0
	s_add_u32 s72, s72, 0x100
	s_addc_u32 s73, s73, 0
	s_cmp_gt_u32 s8, 29
	s_cbranch_scc0 .Lq_lin_0_loop
	s_branch .Lq_lin_exit
.Lq_lin_1_loop:
	s_add_u32 s2, s72, 0xfff80080
	s_addc_u32 s3, s73, -1
	s_add_i32 s9, 0, 0x10000
	s_cmp_eq_u32 s8, 28
	s_cselect_b32 s75, s7, s3
	s_cselect_b32 s74, s55, s2
	v_add_u32_e32 v142, s9, v162
	s_cselect_b32 s3, s53, vcc_hi
	s_cselect_b32 s2, s89, vcc_lo
	s_add_i32 s26, 0, 0x14000
	v_add_u32_e32 v142, s26, v162
	ds_read_b128 v[190:193], v142
	ds_read_b128 v[194:197], v142 offset:1024
	ds_read_b128 v[198:201], v142 offset:2048
	ds_read_b128 v[202:205], v142 offset:3072
	v_lshl_add_u64 v[142:143], s[72:73], 0, v[136:137]
	s_add_i32 m0, s5, 0xc000
	ds_read_b128 v[206:209], v164
	ds_read_b128 v[210:213], v164 offset:1024
	ds_read_b128 v[214:217], v164 offset:2048
	ds_read_b128 v[218:221], v164 offset:3072
	ds_read_b128 v[222:225], v164 offset:4096
	ds_read_b128 v[226:229], v164 offset:5120
	ds_read_b128 v[230:233], v164 offset:6144
	ds_read_b128 v[234:237], v164 offset:7168
	v_lshl_add_u64 v[142:143], s[72:73], 0, v[134:135]
	s_add_i32 m0, s5, 0xe000
	s_nop 0
	s_waitcnt vmcnt(4)
	s_waitcnt lgkmcnt(0)
	s_barrier
	s_setprio 1
	s_waitcnt lgkmcnt(0)
	s_setprio 0
	s_setprio 1
	v_mfma_f32_16x16x32_bf16 v[116:119], v[190:193], v[206:209], v[116:119]
	v_mfma_f32_16x16x32_bf16 v[112:115], v[198:201], v[206:209], v[112:115]
	v_mfma_f32_16x16x32_bf16 v[100:103], v[190:193], v[214:217], v[100:103]
	v_mfma_f32_16x16x32_bf16 v[96:99], v[198:201], v[214:217], v[96:99]
	v_mfma_f32_16x16x32_bf16 v[84:87], v[190:193], v[222:225], v[84:87]
	v_mfma_f32_16x16x32_bf16 v[80:83], v[198:201], v[222:225], v[80:83]
	v_mfma_f32_16x16x32_bf16 v[68:71], v[190:193], v[230:233], v[68:71]
	v_mfma_f32_16x16x32_bf16 v[64:67], v[198:201], v[230:233], v[64:67]
	v_mfma_f32_16x16x32_bf16 v[116:119], v[194:197], v[210:213], v[116:119]
	v_mfma_f32_16x16x32_bf16 v[112:115], v[202:205], v[210:213], v[112:115]
	v_mfma_f32_16x16x32_bf16 v[100:103], v[194:197], v[218:221], v[100:103]
	v_mfma_f32_16x16x32_bf16 v[96:99], v[202:205], v[218:221], v[96:99]
	v_mfma_f32_16x16x32_bf16 v[84:87], v[194:197], v[226:229], v[84:87]
	v_mfma_f32_16x16x32_bf16 v[80:83], v[202:205], v[226:229], v[80:83]
	v_mfma_f32_16x16x32_bf16 v[68:71], v[194:197], v[234:237], v[68:71]
	v_mfma_f32_16x16x32_bf16 v[64:67], v[202:205], v[234:237], v[64:67]
	s_setprio 0
	s_barrier
	s_add_i32 s9, s9, s61
	v_lshl_add_u64 v[142:143], s[2:3], 0, v[144:145]
	s_mov_b32 m0, s9
	s_add_i32 m0, s9, 0x2000
	s_add_u32 s24, s2, 0x80000
	v_lshl_add_u64 v[160:161], s[2:3], 0, v[128:129]
	s_addc_u32 s25, s3, 0
	s_add_i32 s9, s26, s61
	v_lshl_add_u64 v[178:179], s[24:25], 0, v[144:145]
	s_mov_b32 m0, s9
	v_lshl_add_u64 v[238:239], s[74:75], 0, v[130:131]
	global_load_lds_dwordx4 v[178:179], off
	v_lshl_add_u64 v[178:179], s[24:25], 0, v[128:129]
	s_add_i32 m0, s9, 0x2000
	s_nop 0
	global_load_lds_dwordx4 v[178:179], off
	v_lshl_add_u64 v[178:179], s[74:75], 0, v[132:133]
	s_mov_b32 m0, s5
	s_nop 0
	global_load_lds_dwordx4 v[178:179], off
	s_mov_b32 m0, s63
	s_nop 0
	global_load_lds_dwordx4 v[238:239], off
	s_waitcnt vmcnt(4)
	s_waitcnt lgkmcnt(0)
	s_barrier
	s_setprio 1
	s_waitcnt lgkmcnt(0)
	s_setprio 0
	s_setprio 1
	s_setprio 0
	s_barrier
	s_add_i32 s9, 0, 0x18000
	v_add_u32_e32 v165, s9, v162
	s_add_i32 s26, 0, 0x1c000
	v_add_u32_e32 v165, s26, v162
	ds_read_b128 v[190:193], v165
	ds_read_b128 v[194:197], v165 offset:1024
	ds_read_b128 v[198:201], v165 offset:2048
	ds_read_b128 v[202:205], v165 offset:3072
	s_add_u32 s24, s74, 0x80000
	s_addc_u32 s25, s75, 0
	s_mov_b32 m0, s64
	v_lshl_add_u64 v[240:241], s[24:25], 0, v[132:133]
	ds_read_b128 v[206:209], v164 offset:32768
	ds_read_b128 v[210:213], v164 offset:33792
	ds_read_b128 v[214:217], v164 offset:34816
	ds_read_b128 v[218:221], v164 offset:35840
	ds_read_b128 v[222:225], v164 offset:36864
	ds_read_b128 v[226:229], v164 offset:37888
	ds_read_b128 v[230:233], v164 offset:38912
	ds_read_b128 v[234:237], v164 offset:39936
	v_lshl_add_u64 v[240:241], s[24:25], 0, v[130:131]
	s_mov_b32 m0, s65
	s_nop 0
	s_waitcnt vmcnt(4)
	s_waitcnt lgkmcnt(0)
	s_barrier
	s_setprio 1
	s_waitcnt lgkmcnt(0)
	s_setprio 0
	s_setprio 1
	v_mfma_f32_16x16x32_bf16 v[116:119], v[190:193], v[206:209], v[116:119]
	v_mfma_f32_16x16x32_bf16 v[112:115], v[198:201], v[206:209], v[112:115]
	v_mfma_f32_16x16x32_bf16 v[100:103], v[190:193], v[214:217], v[100:103]
	v_mfma_f32_16x16x32_bf16 v[96:99], v[198:201], v[214:217], v[96:99]
	v_mfma_f32_16x16x32_bf16 v[84:87], v[190:193], v[222:225], v[84:87]
	v_mfma_f32_16x16x32_bf16 v[80:83], v[198:201], v[222:225], v[80:83]
	v_mfma_f32_16x16x32_bf16 v[68:71], v[190:193], v[230:233], v[68:71]
	v_mfma_f32_16x16x32_bf16 v[64:67], v[198:201], v[230:233], v[64:67]
	v_mfma_f32_16x16x32_bf16 v[116:119], v[194:197], v[210:213], v[116:119]
	v_mfma_f32_16x16x32_bf16 v[112:115], v[202:205], v[210:213], v[112:115]
	v_mfma_f32_16x16x32_bf16 v[100:103], v[194:197], v[218:221], v[100:103]
	v_mfma_f32_16x16x32_bf16 v[96:99], v[202:205], v[218:221], v[96:99]
	v_mfma_f32_16x16x32_bf16 v[84:87], v[194:197], v[226:229], v[84:87]
	v_mfma_f32_16x16x32_bf16 v[80:83], v[202:205], v[226:229], v[80:83]
	v_mfma_f32_16x16x32_bf16 v[68:71], v[194:197], v[234:237], v[68:71]
	v_mfma_f32_16x16x32_bf16 v[64:67], v[202:205], v[234:237], v[64:67]
	s_setprio 0
	s_barrier
	s_add_i32 s9, s9, s61
	v_lshl_add_u64 v[142:143], v[142:143], 0, s[94:95]
	s_mov_b32 m0, s9
	s_add_i32 m0, s9, 0x2000
	s_add_u32 s2, s2, 0x80080
	v_lshl_add_u64 v[142:143], v[160:161], 0, s[94:95]
	s_addc_u32 s3, s3, 0
	s_add_i32 s9, s26, s61
	v_lshl_add_u64 v[142:143], s[2:3], 0, v[144:145]
	s_mov_b32 m0, s9
	s_nop 0
	global_load_lds_dwordx4 v[142:143], off
	v_lshl_add_u64 v[142:143], s[2:3], 0, v[128:129]
	s_add_i32 m0, s9, 0x2000
	s_nop 0
	global_load_lds_dwordx4 v[142:143], off
	v_lshl_add_u64 v[142:143], v[178:179], 0, s[94:95]
	s_mov_b32 m0, s66
	s_nop 0
	global_load_lds_dwordx4 v[142:143], off
	v_lshl_add_u64 v[142:143], v[238:239], 0, s[94:95]
	s_mov_b32 m0, s84
	s_nop 0
	global_load_lds_dwordx4 v[142:143], off
	s_waitcnt vmcnt(4)
	s_waitcnt lgkmcnt(0)
	s_barrier
	s_setprio 1
	s_waitcnt lgkmcnt(0)
	s_setprio 0
	s_setprio 1
	s_setprio 0
	s_barrier
	s_add_i32 s8, s8, 2
	s_add_u32 vcc_lo, vcc_lo, 0x100
	s_addc_u32 vcc_hi, vcc_hi, 0
	s_add_u32 s72, s72, 0x100
	s_addc_u32 s73, s73, 0
	s_cmp_gt_u32 s8, 29
	s_cbranch_scc0 .Lq_lin_1_loop
	s_branch .Lq_lin_exit
.Lq_lin_2_loop:
	s_add_u32 s2, s72, 0xfff80080
	s_addc_u32 s3, s73, -1
	s_add_i32 s9, 0, 0x10000
	s_cmp_eq_u32 s8, 28
	s_cselect_b32 s75, s7, s3
	s_cselect_b32 s74, s55, s2
	v_add_u32_e32 v142, s9, v162
	s_cselect_b32 s3, s53, vcc_hi
	s_cselect_b32 s2, s89, vcc_lo
	s_add_i32 s26, 0, 0x14000
	ds_read_b128 v[138:141], v142
	ds_read_b128 v[166:169], v142 offset:1024
	ds_read_b128 v[170:173], v142 offset:2048
	ds_read_b128 v[174:177], v142 offset:3072
	v_add_u32_e32 v142, s26, v162
	v_lshl_add_u64 v[142:143], s[72:73], 0, v[136:137]
	s_add_i32 m0, s5, 0xc000
	s_nop 0
	global_load_lds_dwordx4 v[142:143], off
	v_lshl_add_u64 v[142:143], s[72:73], 0, v[134:135]
	s_add_i32 m0, s5, 0xe000
	s_nop 0
	global_load_lds_dwordx4 v[142:143], off
	s_waitcnt vmcnt(4)
	s_waitcnt lgkmcnt(0)
	s_barrier
	s_setprio 1
	s_waitcnt lgkmcnt(0)
	s_setprio 0
	s_setprio 1
	s_setprio 0
	s_barrier
	s_add_i32 s9, s9, s61
	v_lshl_add_u64 v[142:143], s[2:3], 0, v[144:145]
	s_mov_b32 m0, s9
	ds_read_b128 v[206:209], v164 offset:16384
	ds_read_b128 v[210:213], v164 offset:17408
	ds_read_b128 v[214:217], v164 offset:18432
	ds_read_b128 v[218:221], v164 offset:19456
	ds_read_b128 v[222:225], v164 offset:20480
	ds_read_b128 v[226:229], v164 offset:21504
	ds_read_b128 v[230:233], v164 offset:22528
	ds_read_b128 v[234:237], v164 offset:23552
	global_load_lds_dwordx4 v[142:143], off
	s_add_i32 m0, s9, 0x2000
	s_add_u32 s24, s2, 0x80000
	v_lshl_add_u64 v[160:161], s[2:3], 0, v[128:129]
	s_addc_u32 s25, s3, 0
	s_add_i32 s9, s26, s61
	global_load_lds_dwordx4 v[160:161], off
	v_lshl_add_u64 v[178:179], s[24:25], 0, v[144:145]
	s_mov_b32 m0, s9
	v_lshl_add_u64 v[238:239], s[74:75], 0, v[130:131]
	v_lshl_add_u64 v[178:179], s[24:25], 0, v[128:129]
	s_add_i32 m0, s9, 0x2000
	s_nop 0
	v_lshl_add_u64 v[178:179], s[74:75], 0, v[132:133]
	s_mov_b32 m0, s5
	s_nop 0
	s_mov_b32 m0, s63
	s_nop 0
	s_waitcnt vmcnt(4)
	s_waitcnt lgkmcnt(0)
	s_barrier
	s_setprio 1
	s_waitcnt lgkmcnt(0)
	v_mfma_f32_16x16x32_bf16 v[60:63], v[138:141], v[206:209], v[60:63]
	v_mfma_f32_16x16x32_bf16 v[56:59], v[170:173], v[206:209], v[56:59]
	v_mfma_f32_16x16x32_bf16 v[44:47], v[138:141], v[214:217], v[44:47]
	v_mfma_f32_16x16x32_bf16 v[40:43], v[170:173], v[214:217], v[40:43]
	v_mfma_f32_16x16x32_bf16 v[28:31], v[138:141], v[222:225], v[28:31]
	v_mfma_f32_16x16x32_bf16 v[24:27], v[170:173], v[222:225], v[24:27]
	v_mfma_f32_16x16x32_bf16 v[12:15], v[138:141], v[230:233], v[12:15]
	v_mfma_f32_16x16x32_bf16 v[8:11], v[170:173], v[230:233], v[8:11]
	v_mfma_f32_16x16x32_bf16 v[60:63], v[166:169], v[210:213], v[60:63]
	v_mfma_f32_16x16x32_bf16 v[56:59], v[174:177], v[210:213], v[56:59]
	v_mfma_f32_16x16x32_bf16 v[44:47], v[166:169], v[218:221], v[44:47]
	v_mfma_f32_16x16x32_bf16 v[40:43], v[174:177], v[218:221], v[40:43]
	v_mfma_f32_16x16x32_bf16 v[28:31], v[166:169], v[226:229], v[28:31]
	v_mfma_f32_16x16x32_bf16 v[24:27], v[174:177], v[226:229], v[24:27]
	v_mfma_f32_16x16x32_bf16 v[12:15], v[166:169], v[234:237], v[12:15]
	v_mfma_f32_16x16x32_bf16 v[8:11], v[174:177], v[234:237], v[8:11]
	s_setprio 0
	s_setprio 1
	s_setprio 0
	s_barrier
	s_add_i32 s9, 0, 0x18000
	v_add_u32_e32 v165, s9, v162
	s_add_i32 s26, 0, 0x1c000
	ds_read_b128 v[138:141], v165
	ds_read_b128 v[166:169], v165 offset:1024
	ds_read_b128 v[170:173], v165 offset:2048
	ds_read_b128 v[174:177], v165 offset:3072
	v_add_u32_e32 v165, s26, v162
	s_add_u32 s24, s74, 0x80000
	s_addc_u32 s25, s75, 0
	s_mov_b32 m0, s64
	v_lshl_add_u64 v[240:241], s[24:25], 0, v[132:133]
	global_load_lds_dwordx4 v[240:241], off
	v_lshl_add_u64 v[240:241], s[24:25], 0, v[130:131]
	s_mov_b32 m0, s65
	s_nop 0
	global_load_lds_dwordx4 v[240:241], off
	s_waitcnt vmcnt(4)
	s_waitcnt lgkmcnt(0)
	s_barrier
	s_setprio 1
	s_waitcnt lgkmcnt(0)
	s_setprio 0
	s_setprio 1
	s_setprio 0
	s_barrier
	s_add_i32 s9, s9, s61
	v_lshl_add_u64 v[142:143], v[142:143], 0, s[94:95]
	s_mov_b32 m0, s9
	ds_read_b128 v[206:209], v164 offset:49152
	ds_read_b128 v[210:213], v164 offset:50176
	ds_read_b128 v[214:217], v164 offset:51200
	ds_read_b128 v[218:221], v164 offset:52224
	ds_read_b128 v[222:225], v164 offset:53248
	ds_read_b128 v[226:229], v164 offset:54272
	ds_read_b128 v[230:233], v164 offset:55296
	ds_read_b128 v[234:237], v164 offset:56320
	global_load_lds_dwordx4 v[142:143], off
	s_add_i32 m0, s9, 0x2000
	s_add_u32 s2, s2, 0x80080
	v_lshl_add_u64 v[142:143], v[160:161], 0, s[94:95]
	s_addc_u32 s3, s3, 0
	s_add_i32 s9, s26, s61
	global_load_lds_dwordx4 v[142:143], off
	v_lshl_add_u64 v[142:143], s[2:3], 0, v[144:145]
	s_mov_b32 m0, s9
	s_nop 0
	v_lshl_add_u64 v[142:143], s[2:3], 0, v[128:129]
	s_add_i32 m0, s9, 0x2000
	s_nop 0
	v_lshl_add_u64 v[142:143], v[178:179], 0, s[94:95]
	s_mov_b32 m0, s66
	s_nop 0
	v_lshl_add_u64 v[142:143], v[238:239], 0, s[94:95]
	s_mov_b32 m0, s84
	s_nop 0
	s_waitcnt vmcnt(4)
	s_waitcnt lgkmcnt(0)
	s_barrier
	s_setprio 1
	s_waitcnt lgkmcnt(0)
	v_mfma_f32_16x16x32_bf16 v[60:63], v[138:141], v[206:209], v[60:63]
	v_mfma_f32_16x16x32_bf16 v[56:59], v[170:173], v[206:209], v[56:59]
	v_mfma_f32_16x16x32_bf16 v[44:47], v[138:141], v[214:217], v[44:47]
	v_mfma_f32_16x16x32_bf16 v[40:43], v[170:173], v[214:217], v[40:43]
	v_mfma_f32_16x16x32_bf16 v[28:31], v[138:141], v[222:225], v[28:31]
	v_mfma_f32_16x16x32_bf16 v[24:27], v[170:173], v[222:225], v[24:27]
	v_mfma_f32_16x16x32_bf16 v[12:15], v[138:141], v[230:233], v[12:15]
	v_mfma_f32_16x16x32_bf16 v[8:11], v[170:173], v[230:233], v[8:11]
	v_mfma_f32_16x16x32_bf16 v[60:63], v[166:169], v[210:213], v[60:63]
	v_mfma_f32_16x16x32_bf16 v[56:59], v[174:177], v[210:213], v[56:59]
	v_mfma_f32_16x16x32_bf16 v[44:47], v[166:169], v[218:221], v[44:47]
	v_mfma_f32_16x16x32_bf16 v[40:43], v[174:177], v[218:221], v[40:43]
	v_mfma_f32_16x16x32_bf16 v[28:31], v[166:169], v[226:229], v[28:31]
	v_mfma_f32_16x16x32_bf16 v[24:27], v[174:177], v[226:229], v[24:27]
	v_mfma_f32_16x16x32_bf16 v[12:15], v[166:169], v[234:237], v[12:15]
	v_mfma_f32_16x16x32_bf16 v[8:11], v[174:177], v[234:237], v[8:11]
	s_setprio 0
	s_setprio 1
	s_setprio 0
	s_barrier
	s_add_i32 s8, s8, 2
	s_add_u32 vcc_lo, vcc_lo, 0x100
	s_addc_u32 vcc_hi, vcc_hi, 0
	s_add_u32 s72, s72, 0x100
	s_addc_u32 s73, s73, 0
	s_cmp_gt_u32 s8, 29
	s_cbranch_scc0 .Lq_lin_2_loop
	s_branch .Lq_lin_exit
.Lq_lin_3_loop:
	s_add_u32 s2, s72, 0xfff80080
	s_addc_u32 s3, s73, -1
	s_add_i32 s9, 0, 0x10000
	s_cmp_eq_u32 s8, 28
	s_cselect_b32 s75, s7, s3
	s_cselect_b32 s74, s55, s2
	v_add_u32_e32 v142, s9, v162
	s_cselect_b32 s3, s53, vcc_hi
	s_cselect_b32 s2, s89, vcc_lo
	s_add_i32 s26, 0, 0x14000
	v_add_u32_e32 v142, s26, v162
	ds_read_b128 v[190:193], v142
	ds_read_b128 v[194:197], v142 offset:1024
	ds_read_b128 v[198:201], v142 offset:2048
	ds_read_b128 v[202:205], v142 offset:3072
	v_lshl_add_u64 v[142:143], s[72:73], 0, v[136:137]
	s_add_i32 m0, s5, 0xc000
	s_nop 0
	global_load_lds_dwordx4 v[142:143], off
	v_lshl_add_u64 v[142:143], s[72:73], 0, v[134:135]
	s_add_i32 m0, s5, 0xe000
	s_nop 0
	global_load_lds_dwordx4 v[142:143], off
	s_waitcnt vmcnt(4)
	s_waitcnt lgkmcnt(0)
	s_barrier
	s_setprio 1
	s_waitcnt lgkmcnt(0)
	s_setprio 0
	s_setprio 1
	s_setprio 0
	s_barrier
	s_add_i32 s9, s9, s61
	v_lshl_add_u64 v[142:143], s[2:3], 0, v[144:145]
	s_mov_b32 m0, s9
	ds_read_b128 v[206:209], v164 offset:16384
	ds_read_b128 v[210:213], v164 offset:17408
	ds_read_b128 v[214:217], v164 offset:18432
	ds_read_b128 v[218:221], v164 offset:19456
	ds_read_b128 v[222:225], v164 offset:20480
	ds_read_b128 v[226:229], v164 offset:21504
	ds_read_b128 v[230:233], v164 offset:22528
	ds_read_b128 v[234:237], v164 offset:23552
	s_add_i32 m0, s9, 0x2000
	s_add_u32 s24, s2, 0x80000
	v_lshl_add_u64 v[160:161], s[2:3], 0, v[128:129]
	s_addc_u32 s25, s3, 0
	s_add_i32 s9, s26, s61
	v_lshl_add_u64 v[178:179], s[24:25], 0, v[144:145]
	s_mov_b32 m0, s9
	v_lshl_add_u64 v[238:239], s[74:75], 0, v[130:131]
	global_load_lds_dwordx4 v[178:179], off
	v_lshl_add_u64 v[178:179], s[24:25], 0, v[128:129]
	s_add_i32 m0, s9, 0x2000
	s_nop 0
	global_load_lds_dwordx4 v[178:179], off
	v_lshl_add_u64 v[178:179], s[74:75], 0, v[132:133]
	s_mov_b32 m0, s5
	s_nop 0
	s_mov_b32 m0, s63
	s_nop 0
	s_waitcnt vmcnt(4)
	s_waitcnt lgkmcnt(0)
	s_barrier
	s_setprio 1
	s_waitcnt lgkmcnt(0)
	s_setprio 0
	s_setprio 1
	v_mfma_f32_16x16x32_bf16 v[52:55], v[190:193], v[206:209], v[52:55]
	v_mfma_f32_16x16x32_bf16 v[48:51], v[198:201], v[206:209], v[48:51]
	v_mfma_f32_16x16x32_bf16 v[36:39], v[190:193], v[214:217], v[36:39]
	v_mfma_f32_16x16x32_bf16 v[32:35], v[198:201], v[214:217], v[32:35]
	v_mfma_f32_16x16x32_bf16 v[20:23], v[190:193], v[222:225], v[20:23]
	v_mfma_f32_16x16x32_bf16 v[16:19], v[198:201], v[222:225], v[16:19]
	v_mfma_f32_16x16x32_bf16 v[4:7], v[190:193], v[230:233], v[4:7]
	v_mfma_f32_16x16x32_bf16 v[0:3], v[198:201], v[230:233], v[0:3]
	v_mfma_f32_16x16x32_bf16 v[52:55], v[194:197], v[210:213], v[52:55]
	v_mfma_f32_16x16x32_bf16 v[48:51], v[202:205], v[210:213], v[48:51]
	v_mfma_f32_16x16x32_bf16 v[36:39], v[194:197], v[218:221], v[36:39]
	v_mfma_f32_16x16x32_bf16 v[32:35], v[202:205], v[218:221], v[32:35]
	v_mfma_f32_16x16x32_bf16 v[20:23], v[194:197], v[226:229], v[20:23]
	v_mfma_f32_16x16x32_bf16 v[16:19], v[202:205], v[226:229], v[16:19]
	v_mfma_f32_16x16x32_bf16 v[4:7], v[194:197], v[234:237], v[4:7]
	v_mfma_f32_16x16x32_bf16 v[0:3], v[202:205], v[234:237], v[0:3]
	s_setprio 0
	s_barrier
	s_add_i32 s9, 0, 0x18000
	v_add_u32_e32 v165, s9, v162
	s_add_i32 s26, 0, 0x1c000
	v_add_u32_e32 v165, s26, v162
	ds_read_b128 v[190:193], v165
	ds_read_b128 v[194:197], v165 offset:1024
	ds_read_b128 v[198:201], v165 offset:2048
	ds_read_b128 v[202:205], v165 offset:3072
	s_add_u32 s24, s74, 0x80000
	s_addc_u32 s25, s75, 0
	s_mov_b32 m0, s64
	v_lshl_add_u64 v[240:241], s[24:25], 0, v[132:133]
	global_load_lds_dwordx4 v[240:241], off
	v_lshl_add_u64 v[240:241], s[24:25], 0, v[130:131]
	s_mov_b32 m0, s65
	s_nop 0
	global_load_lds_dwordx4 v[240:241], off
	s_waitcnt vmcnt(4)
	s_waitcnt lgkmcnt(0)
	s_barrier
	s_setprio 1
	s_waitcnt lgkmcnt(0)
	s_setprio 0
	s_setprio 1
	s_setprio 0
	s_barrier
	s_add_i32 s9, s9, s61
	v_lshl_add_u64 v[142:143], v[142:143], 0, s[94:95]
	s_mov_b32 m0, s9
	ds_read_b128 v[206:209], v164 offset:49152
	ds_read_b128 v[210:213], v164 offset:50176
	ds_read_b128 v[214:217], v164 offset:51200
	ds_read_b128 v[218:221], v164 offset:52224
	ds_read_b128 v[222:225], v164 offset:53248
	ds_read_b128 v[226:229], v164 offset:54272
	ds_read_b128 v[230:233], v164 offset:55296
	ds_read_b128 v[234:237], v164 offset:56320
	s_add_i32 m0, s9, 0x2000
	s_add_u32 s2, s2, 0x80080
	v_lshl_add_u64 v[142:143], v[160:161], 0, s[94:95]
	s_addc_u32 s3, s3, 0
	s_add_i32 s9, s26, s61
	v_lshl_add_u64 v[142:143], s[2:3], 0, v[144:145]
	s_mov_b32 m0, s9
	s_nop 0
	global_load_lds_dwordx4 v[142:143], off
	v_lshl_add_u64 v[142:143], s[2:3], 0, v[128:129]
	s_add_i32 m0, s9, 0x2000
	s_nop 0
	global_load_lds_dwordx4 v[142:143], off
	v_lshl_add_u64 v[142:143], v[178:179], 0, s[94:95]
	s_mov_b32 m0, s66
	s_nop 0
	v_lshl_add_u64 v[142:143], v[238:239], 0, s[94:95]
	s_mov_b32 m0, s84
	s_nop 0
	s_waitcnt vmcnt(4)
	s_waitcnt lgkmcnt(0)
	s_barrier
	s_setprio 1
	s_waitcnt lgkmcnt(0)
	s_setprio 0
	s_setprio 1
	v_mfma_f32_16x16x32_bf16 v[52:55], v[190:193], v[206:209], v[52:55]
	v_mfma_f32_16x16x32_bf16 v[48:51], v[198:201], v[206:209], v[48:51]
	v_mfma_f32_16x16x32_bf16 v[36:39], v[190:193], v[214:217], v[36:39]
	v_mfma_f32_16x16x32_bf16 v[32:35], v[198:201], v[214:217], v[32:35]
	v_mfma_f32_16x16x32_bf16 v[20:23], v[190:193], v[222:225], v[20:23]
	v_mfma_f32_16x16x32_bf16 v[16:19], v[198:201], v[222:225], v[16:19]
	v_mfma_f32_16x16x32_bf16 v[4:7], v[190:193], v[230:233], v[4:7]
	v_mfma_f32_16x16x32_bf16 v[0:3], v[198:201], v[230:233], v[0:3]
	v_mfma_f32_16x16x32_bf16 v[52:55], v[194:197], v[210:213], v[52:55]
	v_mfma_f32_16x16x32_bf16 v[48:51], v[202:205], v[210:213], v[48:51]
	v_mfma_f32_16x16x32_bf16 v[36:39], v[194:197], v[218:221], v[36:39]
	v_mfma_f32_16x16x32_bf16 v[32:35], v[202:205], v[218:221], v[32:35]
	v_mfma_f32_16x16x32_bf16 v[20:23], v[194:197], v[226:229], v[20:23]
	v_mfma_f32_16x16x32_bf16 v[16:19], v[202:205], v[226:229], v[16:19]
	v_mfma_f32_16x16x32_bf16 v[4:7], v[194:197], v[234:237], v[4:7]
	v_mfma_f32_16x16x32_bf16 v[0:3], v[202:205], v[234:237], v[0:3]
	s_setprio 0
	s_barrier
	s_add_i32 s8, s8, 2
	s_add_u32 vcc_lo, vcc_lo, 0x100
	s_addc_u32 vcc_hi, vcc_hi, 0
	s_add_u32 s72, s72, 0x100
	s_addc_u32 s73, s73, 0
	s_cmp_gt_u32 s8, 29
	s_cbranch_scc0 .Lq_lin_3_loop
	s_branch .Lq_lin_exit
.Lq_lin_exit:
	s_and_b64 vcc, exec, s[40:41]
	s_cbranch_vccz .LBB0_118
	s_barrier
.LBB0_118:
	v_lshl_add_u32 v142, s4, 8, v146
	v_lshl_or_b32 v138, s6, 8, v163
	v_ashrrev_i32_e32 v143, 31, v142
	v_ashrrev_i32_e32 v139, 31, v138
	v_lshlrev_b64 v[140:141], 13, v[142:143]
	v_lshl_add_u64 v[140:141], s[34:35], 0, v[140:141]
	v_lshlrev_b64 v[160:161], 1, v[138:139]
	v_lshl_add_u64 v[138:139], v[140:141], 0, v[160:161]
	v_lshl_add_u64 v[140:141], v[142:143], 2, s[38:39]
	global_load_dword v200, v[140:141], off
	global_load_dword v201, v[140:141], off offset:64
	global_load_dword v202, v[140:141], off offset:128
	global_load_dword v203, v[140:141], off offset:192
	global_load_dword v204, v[140:141], off offset:512
	global_load_dword v205, v[140:141], off offset:576
	global_load_dword v206, v[140:141], off offset:640
	global_load_dword v207, v[140:141], off offset:704
	s_waitcnt vmcnt(0)
	v_mov_b32_e32 v143, v200
	s_mov_b32 s2, 0x100000
	s_mov_b32 s89, 0x18000
	v_fmamk_f32 v143, v143, 0x3a000000, v181
	v_cmp_gt_f32_e32 vcc, s80, v143
	v_mul_f32_e32 v165, 0x4b800000, v143
	s_nop 0
	v_cndmask_b32_e32 v143, v143, v165, vcc
	v_rsq_f32_e32 v143, v143
	s_nop 0
	v_mul_f32_e32 v165, 0x45800000, v143
	v_cndmask_b32_e32 v166, v143, v165, vcc
	v_pk_mul_f32 v[126:127], v[126:127], v[166:167] op_sel_hi:[1,0]
	v_pk_mul_f32 v[124:125], v[124:125], v[166:167] op_sel_hi:[1,0]
	v_pk_mul_f32 v[168:169], v[122:123], v[166:167] op_sel_hi:[1,0]
	v_pk_mul_f32 v[122:123], v[120:121], v[166:167] op_sel_hi:[1,0]
	v_cvt_pk_bf16_f32 v120, v124, v125
	v_cvt_pk_bf16_f32 v121, v126, v127
	v_pk_mul_f32 v[116:117], v[116:117], v[166:167] op_sel_hi:[1,0]
	v_cvt_pk_bf16_f32 v122, v122, v123
	v_cvt_pk_bf16_f32 v123, v168, v169
	s_bitcmp1_b32 s100, 0
	s_cbranch_scc0 .Lq_lin_e0
	flat_store_dwordx4 v[138:139], v[120:123]
.Lq_lin_e0:
	v_pk_mul_f32 v[118:119], v[118:119], v[166:167] op_sel_hi:[1,0]
	s_nop 0
	v_pk_mul_f32 v[120:121], v[114:115], v[166:167] op_sel_hi:[1,0]
	v_pk_mul_f32 v[114:115], v[112:113], v[166:167] op_sel_hi:[1,0]
	v_cvt_pk_bf16_f32 v112, v116, v117
	v_cvt_pk_bf16_f32 v113, v118, v119
	s_nop 0
	v_cvt_pk_bf16_f32 v114, v114, v115
	v_cvt_pk_bf16_f32 v115, v120, v121
	s_bitcmp1_b32 s100, 1
	s_cbranch_scc0 .Lq_lin_e1
	flat_store_dwordx4 v[138:139], v[112:115] offset:256
.Lq_lin_e1:
	s_nop 1
	v_or_b32_e32 v112, 16, v142
	v_ashrrev_i32_e32 v113, 31, v112
	v_lshlrev_b64 v[114:115], 13, v[112:113]
	v_lshl_add_u64 v[112:113], v[112:113], 2, s[38:39]
	s_nop 1
	v_mov_b32_e32 v112, v201
	v_lshl_add_u64 v[114:115], s[34:35], 0, v[114:115]
	v_lshl_add_u64 v[114:115], v[114:115], 0, v[160:161]
	v_fmamk_f32 v112, v112, 0x3a000000, v181
	v_cmp_gt_f32_e32 vcc, s80, v112
	v_mul_f32_e32 v113, 0x4b800000, v112
	s_nop 0
	v_cndmask_b32_e32 v112, v112, v113, vcc
	v_rsq_f32_e32 v112, v112
	s_nop 0
	v_mul_f32_e32 v113, 0x45800000, v112
	v_cndmask_b32_e32 v112, v112, v113, vcc
	v_pk_mul_f32 v[110:111], v[110:111], v[112:113] op_sel_hi:[1,0]
	v_pk_mul_f32 v[108:109], v[108:109], v[112:113] op_sel_hi:[1,0]
	v_pk_mul_f32 v[116:117], v[106:107], v[112:113] op_sel_hi:[1,0]
	v_pk_mul_f32 v[106:107], v[104:105], v[112:113] op_sel_hi:[1,0]
	v_cvt_pk_bf16_f32 v104, v108, v109
	v_cvt_pk_bf16_f32 v105, v110, v111
	v_pk_mul_f32 v[100:101], v[100:101], v[112:113] op_sel_hi:[1,0]
	v_cvt_pk_bf16_f32 v106, v106, v107
	v_cvt_pk_bf16_f32 v107, v116, v117
	s_bitcmp1_b32 s100, 0
	s_cbranch_scc0 .Lq_lin_e2
	flat_store_dwordx4 v[114:115], v[104:107]
.Lq_lin_e2:
	v_pk_mul_f32 v[102:103], v[102:103], v[112:113] op_sel_hi:[1,0]
	s_nop 0
	v_pk_mul_f32 v[104:105], v[98:99], v[112:113] op_sel_hi:[1,0]
	v_pk_mul_f32 v[98:99], v[96:97], v[112:113] op_sel_hi:[1,0]
	v_cvt_pk_bf16_f32 v96, v100, v101
	v_cvt_pk_bf16_f32 v97, v102, v103
	s_nop 0
	v_cvt_pk_bf16_f32 v98, v98, v99
	v_cvt_pk_bf16_f32 v99, v104, v105
	s_bitcmp1_b32 s100, 1
	s_cbranch_scc0 .Lq_lin_e3
	flat_store_dwordx4 v[114:115], v[96:99] offset:256
.Lq_lin_e3:
	s_nop 1
	v_or_b32_e32 v96, 32, v142
	v_ashrrev_i32_e32 v97, 31, v96
	v_lshlrev_b64 v[98:99], 13, v[96:97]
	v_lshl_add_u64 v[96:97], v[96:97], 2, s[38:39]
	s_nop 1
	v_mov_b32_e32 v96, v202
	v_lshl_add_u64 v[98:99], s[34:35], 0, v[98:99]
	v_lshl_add_u64 v[98:99], v[98:99], 0, v[160:161]
	v_fmamk_f32 v96, v96, 0x3a000000, v181
	v_cmp_gt_f32_e32 vcc, s80, v96
	v_mul_f32_e32 v97, 0x4b800000, v96
	s_nop 0
	v_cndmask_b32_e32 v96, v96, v97, vcc
	v_rsq_f32_e32 v96, v96
	s_nop 0
	v_mul_f32_e32 v97, 0x45800000, v96
	v_cndmask_b32_e32 v96, v96, v97, vcc
	v_pk_mul_f32 v[94:95], v[94:95], v[96:97] op_sel_hi:[1,0]
	v_pk_mul_f32 v[92:93], v[92:93], v[96:97] op_sel_hi:[1,0]
	v_pk_mul_f32 v[100:101], v[90:91], v[96:97] op_sel_hi:[1,0]
	v_pk_mul_f32 v[90:91], v[88:89], v[96:97] op_sel_hi:[1,0]
	v_cvt_pk_bf16_f32 v88, v92, v93
	v_cvt_pk_bf16_f32 v89, v94, v95
	v_pk_mul_f32 v[84:85], v[84:85], v[96:97] op_sel_hi:[1,0]
	v_cvt_pk_bf16_f32 v90, v90, v91
	v_cvt_pk_bf16_f32 v91, v100, v101
	s_bitcmp1_b32 s100, 0
	s_cbranch_scc0 .Lq_lin_e4
	flat_store_dwordx4 v[98:99], v[88:91]
.Lq_lin_e4:
	v_pk_mul_f32 v[86:87], v[86:87], v[96:97] op_sel_hi:[1,0]
	s_nop 0
	v_pk_mul_f32 v[88:89], v[82:83], v[96:97] op_sel_hi:[1,0]
	v_pk_mul_f32 v[82:83], v[80:81], v[96:97] op_sel_hi:[1,0]
	v_cvt_pk_bf16_f32 v80, v84, v85
	v_cvt_pk_bf16_f32 v81, v86, v87
	s_nop 0
	v_cvt_pk_bf16_f32 v82, v82, v83
	v_cvt_pk_bf16_f32 v83, v88, v89
	s_bitcmp1_b32 s100, 1
	s_cbranch_scc0 .Lq_lin_e5
	flat_store_dwordx4 v[98:99], v[80:83] offset:256
.Lq_lin_e5:
	s_nop 1
	v_or_b32_e32 v80, 48, v142
	v_ashrrev_i32_e32 v81, 31, v80
	v_lshlrev_b64 v[82:83], 13, v[80:81]
	v_lshl_add_u64 v[80:81], v[80:81], 2, s[38:39]
	s_nop 1
	v_mov_b32_e32 v80, v203
	v_lshl_add_u64 v[82:83], s[34:35], 0, v[82:83]
	v_lshl_add_u64 v[82:83], v[82:83], 0, v[160:161]
	v_fmamk_f32 v80, v80, 0x3a000000, v181
	v_cmp_gt_f32_e32 vcc, s80, v80
	v_mul_f32_e32 v81, 0x4b800000, v80
	s_nop 0
	v_cndmask_b32_e32 v80, v80, v81, vcc
	v_rsq_f32_e32 v80, v80
	s_nop 0
	v_mul_f32_e32 v81, 0x45800000, v80
	v_cndmask_b32_e32 v80, v80, v81, vcc
	v_pk_mul_f32 v[78:79], v[78:79], v[80:81] op_sel_hi:[1,0]
	v_pk_mul_f32 v[76:77], v[76:77], v[80:81] op_sel_hi:[1,0]
	v_pk_mul_f32 v[84:85], v[74:75], v[80:81] op_sel_hi:[1,0]
	v_pk_mul_f32 v[74:75], v[72:73], v[80:81] op_sel_hi:[1,0]
	v_cvt_pk_bf16_f32 v72, v76, v77
	v_cvt_pk_bf16_f32 v73, v78, v79
	v_pk_mul_f32 v[70:71], v[70:71], v[80:81] op_sel_hi:[1,0]
	v_cvt_pk_bf16_f32 v74, v74, v75
	v_cvt_pk_bf16_f32 v75, v84, v85
	s_bitcmp1_b32 s100, 0
	s_cbranch_scc0 .Lq_lin_e6
	flat_store_dwordx4 v[82:83], v[72:75]
.Lq_lin_e6:
	v_pk_mul_f32 v[68:69], v[68:69], v[80:81] op_sel_hi:[1,0]
	s_nop 0
	v_pk_mul_f32 v[72:73], v[66:67], v[80:81] op_sel_hi:[1,0]
	v_pk_mul_f32 v[66:67], v[64:65], v[80:81] op_sel_hi:[1,0]
	v_cvt_pk_bf16_f32 v64, v68, v69
	v_cvt_pk_bf16_f32 v65, v70, v71
	s_nop 0
	v_cvt_pk_bf16_f32 v66, v66, v67
	v_cvt_pk_bf16_f32 v67, v72, v73
	s_bitcmp1_b32 s100, 1
	s_cbranch_scc0 .Lq_lin_e7
	flat_store_dwordx4 v[82:83], v[64:67] offset:256
.Lq_lin_e7:
	s_nop 1
	v_mov_b32_e32 v66, v204
	s_nop 0
	v_lshl_add_u64 v[64:65], v[138:139], 0, s[96:97]
	v_fmamk_f32 v66, v66, 0x3a000000, v181
	v_cmp_gt_f32_e32 vcc, s80, v66
	v_mul_f32_e32 v67, 0x4b800000, v66
	s_nop 0
	v_cndmask_b32_e32 v66, v66, v67, vcc
	v_rsq_f32_e32 v66, v66
	s_nop 0
	v_mul_f32_e32 v67, 0x45800000, v66
	v_cndmask_b32_e32 v66, v66, v67, vcc
	v_pk_mul_f32 v[60:61], v[60:61], v[66:67] op_sel_hi:[1,0]
	v_pk_mul_f32 v[68:69], v[58:59], v[66:67] op_sel_hi:[1,0]
	v_pk_mul_f32 v[58:59], v[56:57], v[66:67] op_sel_hi:[1,0]
	v_cvt_pk_bf16_f32 v56, v60, v61
	v_add_co_u32_e32 v60, vcc, s2, v138
	v_pk_mul_f32 v[62:63], v[62:63], v[66:67] op_sel_hi:[1,0]
	s_nop 0
	v_addc_co_u32_e32 v61, vcc, 0, v139, vcc
	v_cvt_pk_bf16_f32 v57, v62, v63
	v_cvt_pk_bf16_f32 v58, v58, v59
	v_cvt_pk_bf16_f32 v59, v68, v69
	s_bitcmp1_b32 s100, 2
	s_cbranch_scc0 .Lq_lin_e8
	flat_store_dwordx4 v[60:61], v[56:59]
.Lq_lin_e8:
	v_pk_mul_f32 v[54:55], v[54:55], v[66:67] op_sel_hi:[1,0]
	v_pk_mul_f32 v[52:53], v[52:53], v[66:67] op_sel_hi:[1,0]
	v_pk_mul_f32 v[56:57], v[50:51], v[66:67] op_sel_hi:[1,0]
	v_pk_mul_f32 v[50:51], v[48:49], v[66:67] op_sel_hi:[1,0]
	v_cvt_pk_bf16_f32 v48, v52, v53
	v_cvt_pk_bf16_f32 v49, v54, v55
	s_mov_b64 s[2:3], 0x120000
	v_cvt_pk_bf16_f32 v50, v50, v51
	v_cvt_pk_bf16_f32 v51, v56, v57
	s_bitcmp1_b32 s100, 3
	s_cbranch_scc0 .Lq_lin_e9
	flat_store_dwordx4 v[64:65], v[48:51] offset:256
.Lq_lin_e9:
	s_nop 1
	v_mov_b32_e32 v50, v205
	s_nop 0
	v_lshl_add_u64 v[48:49], v[138:139], 0, s[2:3]
	s_mov_b32 s2, 0x120000
	v_fmamk_f32 v50, v50, 0x3a000000, v181
	v_cmp_gt_f32_e32 vcc, s80, v50
	v_mul_f32_e32 v51, 0x4b800000, v50
	s_nop 0
	v_cndmask_b32_e32 v50, v50, v51, vcc
	v_rsq_f32_e32 v50, v50
	s_nop 0
	v_mul_f32_e32 v51, 0x45800000, v50
	v_cndmask_b32_e32 v50, v50, v51, vcc
	v_pk_mul_f32 v[44:45], v[44:45], v[50:51] op_sel_hi:[1,0]
	v_pk_mul_f32 v[52:53], v[42:43], v[50:51] op_sel_hi:[1,0]
	v_pk_mul_f32 v[42:43], v[40:41], v[50:51] op_sel_hi:[1,0]
	v_cvt_pk_bf16_f32 v40, v44, v45
	v_add_co_u32_e32 v44, vcc, s2, v138
	v_pk_mul_f32 v[46:47], v[46:47], v[50:51] op_sel_hi:[1,0]
	s_nop 0
	v_addc_co_u32_e32 v45, vcc, 0, v139, vcc
	v_cvt_pk_bf16_f32 v41, v46, v47
	v_cvt_pk_bf16_f32 v42, v42, v43
	v_cvt_pk_bf16_f32 v43, v52, v53
	s_bitcmp1_b32 s100, 2
	s_cbranch_scc0 .Lq_lin_e10
	flat_store_dwordx4 v[44:45], v[40:43]
.Lq_lin_e10:
	v_pk_mul_f32 v[38:39], v[38:39], v[50:51] op_sel_hi:[1,0]
	v_pk_mul_f32 v[36:37], v[36:37], v[50:51] op_sel_hi:[1,0]
	v_pk_mul_f32 v[40:41], v[34:35], v[50:51] op_sel_hi:[1,0]
	v_pk_mul_f32 v[34:35], v[32:33], v[50:51] op_sel_hi:[1,0]
	v_cvt_pk_bf16_f32 v32, v36, v37
	v_cvt_pk_bf16_f32 v33, v38, v39
	s_mov_b64 s[2:3], 0x140000
	v_cvt_pk_bf16_f32 v34, v34, v35
	v_cvt_pk_bf16_f32 v35, v40, v41
	s_bitcmp1_b32 s100, 3
	s_cbranch_scc0 .Lq_lin_e11
	flat_store_dwordx4 v[48:49], v[32:35] offset:256
.Lq_lin_e11:
	s_nop 1
	v_mov_b32_e32 v34, v206
	s_nop 0
	v_lshl_add_u64 v[32:33], v[138:139], 0, s[2:3]
	s_mov_b32 s2, 0x140000
	v_fmamk_f32 v34, v34, 0x3a000000, v181
	v_cmp_gt_f32_e32 vcc, s80, v34
	v_mul_f32_e32 v35, 0x4b800000, v34
	s_nop 0
	v_cndmask_b32_e32 v34, v34, v35, vcc
	v_rsq_f32_e32 v34, v34
	s_nop 0
	v_mul_f32_e32 v35, 0x45800000, v34
	v_cndmask_b32_e32 v34, v34, v35, vcc
	v_pk_mul_f32 v[28:29], v[28:29], v[34:35] op_sel_hi:[1,0]
	v_pk_mul_f32 v[36:37], v[26:27], v[34:35] op_sel_hi:[1,0]
	v_pk_mul_f32 v[26:27], v[24:25], v[34:35] op_sel_hi:[1,0]
	v_cvt_pk_bf16_f32 v24, v28, v29
	v_add_co_u32_e32 v28, vcc, s2, v138
	v_pk_mul_f32 v[30:31], v[30:31], v[34:35] op_sel_hi:[1,0]
	s_nop 0
	v_addc_co_u32_e32 v29, vcc, 0, v139, vcc
	v_cvt_pk_bf16_f32 v25, v30, v31
	v_cvt_pk_bf16_f32 v26, v26, v27
	v_cvt_pk_bf16_f32 v27, v36, v37
	s_bitcmp1_b32 s100, 2
	s_cbranch_scc0 .Lq_lin_e12
	flat_store_dwordx4 v[28:29], v[24:27]
.Lq_lin_e12:
	v_pk_mul_f32 v[22:23], v[22:23], v[34:35] op_sel_hi:[1,0]
	v_pk_mul_f32 v[20:21], v[20:21], v[34:35] op_sel_hi:[1,0]
	v_pk_mul_f32 v[24:25], v[18:19], v[34:35] op_sel_hi:[1,0]
	v_pk_mul_f32 v[18:19], v[16:17], v[34:35] op_sel_hi:[1,0]
	v_cvt_pk_bf16_f32 v16, v20, v21
	v_cvt_pk_bf16_f32 v17, v22, v23
	s_mov_b64 s[2:3], 0x160000
	v_cvt_pk_bf16_f32 v18, v18, v19
	v_cvt_pk_bf16_f32 v19, v24, v25
	s_bitcmp1_b32 s100, 3
	s_cbranch_scc0 .Lq_lin_e13
	flat_store_dwordx4 v[32:33], v[16:19] offset:256
.Lq_lin_e13:
	s_nop 1
	v_mov_b32_e32 v16, v207
	s_nop 0
	v_lshl_add_u64 v[18:19], v[138:139], 0, s[2:3]
	s_mov_b32 s2, 0x160000
	v_fmamk_f32 v16, v16, 0x3a000000, v181
	v_cmp_gt_f32_e32 vcc, s80, v16
	v_mul_f32_e32 v17, 0x4b800000, v16
	s_nop 0
	v_cndmask_b32_e32 v16, v16, v17, vcc
	v_rsq_f32_e32 v16, v16
	s_nop 0
	v_mul_f32_e32 v17, 0x45800000, v16
	v_cndmask_b32_e32 v16, v16, v17, vcc
	v_pk_mul_f32 v[12:13], v[12:13], v[16:17] op_sel_hi:[1,0]
	v_pk_mul_f32 v[20:21], v[10:11], v[16:17] op_sel_hi:[1,0]
	v_pk_mul_f32 v[10:11], v[8:9], v[16:17] op_sel_hi:[1,0]
	v_cvt_pk_bf16_f32 v8, v12, v13
	v_add_co_u32_e32 v12, vcc, s2, v138
	v_pk_mul_f32 v[14:15], v[14:15], v[16:17] op_sel_hi:[1,0]
	s_nop 0
	v_addc_co_u32_e32 v13, vcc, 0, v139, vcc
	v_cvt_pk_bf16_f32 v9, v14, v15
	v_cvt_pk_bf16_f32 v10, v10, v11
	v_cvt_pk_bf16_f32 v11, v20, v21
	s_bitcmp1_b32 s100, 2
	s_cbranch_scc0 .Lq_lin_e14
	flat_store_dwordx4 v[12:13], v[8:11]
.Lq_lin_e14:
	s_mov_b64 s[2:3], -1
	s_andn2_b64 vcc, exec, s[36:37]
	v_pk_mul_f32 v[8:9], v[2:3], v[16:17] op_sel_hi:[1,0]
	v_pk_mul_f32 v[2:3], v[0:1], v[16:17] op_sel_hi:[1,0]
	v_pk_mul_f32 v[6:7], v[6:7], v[16:17] op_sel_hi:[1,0]
	v_pk_mul_f32 v[4:5], v[4:5], v[16:17] op_sel_hi:[1,0]
	s_nop 0
	v_cvt_pk_bf16_f32 v0, v4, v5
	v_cvt_pk_bf16_f32 v1, v6, v7
	v_cvt_pk_bf16_f32 v2, v2, v3
	v_cvt_pk_bf16_f32 v3, v8, v9
	s_bitcmp1_b32 s100, 3
	s_cbranch_scc0 .Lq_lin_e15
	flat_store_dwordx4 v[18:19], v[0:3] offset:256
.Lq_lin_e15:
	s_cbranch_vccnz .LBB0_111
	s_andn2_b64 vcc, exec, s[30:31]
	s_cbranch_vccnz .LBB0_110
	s_barrier
	s_branch .LBB0_110

.LBB0_620:
	s_mul_i32 s14, s90, 0x2400
	s_mov_b32 s15, s67
	s_add_u32 s30, s12, 0x10d00000
	s_addc_u32 s31, s13, 0
	s_lshl_b64 s[40:41], s[14:15], 2
	s_mov_b32 s24, s14
	s_add_u32 s14, s12, s40
	s_addc_u32 s15, s13, s41
	s_add_u32 s40, s14, 0x7000
	s_addc_u32 s41, s15, 0
	s_lshl_b32 s15, s36, 5
	s_and_b32 s15, s15, 0x60
	s_add_i32 m0, s5, 0x18000
	v_lshl_add_u64 v[6:7], v[6:7], 0, s[94:95]
	s_lshl_b32 s14, s9, 13
	s_lshl_b32 s39, s15, 7
	s_waitcnt vmcnt(2)
	s_barrier
	global_load_lds_dwordx4 v[6:7], off
	v_lshl_add_u64 v[4:5], v[4:5], 0, s[94:95]
	s_add_i32 m0, s5, 0x1a000
	s_add_i32 s61, s5, 0x8000
	s_add_i32 s62, s5, 0xa000
	global_load_lds_dwordx4 v[4:5], off
	v_lshl_add_u64 v[0:1], v[0:1], 0, s[94:95]
	s_mov_b32 m0, s61
	s_add_u32 s36, s2, 0x80080
	global_load_lds_dwordx4 v[0:1], off
	v_lshl_add_u64 v[0:1], v[2:3], 0, s[94:95]
	s_mov_b32 m0, s62
	s_addc_u32 s37, s3, 0
	global_load_lds_dwordx4 v[0:1], off
	s_add_i32 m0, s5, 0x1c000
	v_lshl_add_u64 v[0:1], s[36:37], 0, v[144:145]
	global_load_lds_dwordx4 v[0:1], off
	v_lshl_add_u64 v[0:1], s[36:37], 0, v[132:133]
	s_add_i32 m0, s5, 0x1e000
	v_writelane_b32 v244, s24, 17
	global_load_lds_dwordx4 v[0:1], off
	v_lshrrev_b32_e32 v1, 1, v8
	v_and_b32_e32 v1, 24, v1
	v_and_b32_e32 v0, 15, v8
	v_lshlrev_b32_e32 v2, 1, v1
	v_lshl_or_b32 v143, s9, 6, v0
	v_lshl_or_b32 v0, v0, 6, v2
	v_lshlrev_b32_e32 v2, 2, v8
	v_and_b32_e32 v2, 32, v2
	v_bitop3_b32 v3, v0, s14, v2 bitop3:0xde
	v_bitop3_b32 v160, v0, s39, v2 bitop3:0xde
	v_lshlrev_b32_e32 v0, 15, v12
	v_and_b32_e32 v0, 0xffff0000, v0
	v_or_b32_e32 v161, s15, v1
	v_lshl_add_u32 v0, v13, 12, v0
	v_and_b32_e32 v1, 1, v12
	v_lshl_or_b32 v0, v1, 6, v0
	v_writelane_b32 v244, s25, 18
	s_cmpk_lt_u32 s8, 0x100
	v_lshl_add_u32 v134, v14, 1, v0
	v_lshlrev_b32_e32 v0, 15, v9
	s_cselect_b64 s[52:53], -1, 0
	s_ashr_i32 s63, s6, 31
	v_readlane_b32 s24, v244, 13
	v_and_b32_e32 v0, 0xffff0000, v0
	s_waitcnt vmcnt(6)
	s_cmp_lg_u64 s[40:41], 0
	v_readlane_b32 s25, v244, 14
	v_lshl_add_u32 v0, v10, 12, v0
	v_and_b32_e32 v1, 1, v9
	s_cselect_b64 s[8:9], -1, 0
	s_xor_b64 s[36:37], s[24:25], -1
	v_lshl_or_b32 v0, v1, 6, v0
	s_and_b64 s[54:55], s[36:37], s[8:9]
	v_mov_b32_e32 v135, v145
	v_lshl_add_u32 v136, v11, 1, v0
	v_mov_b32_e32 v137, v145
	s_mov_b32 s64, 0
	v_add_u32_e32 v162, 0, v3
	s_barrier
	s_mov_b32 s100, 15
	s_branch .LBB0_623

.LBB0_622:
	s_mov_b32 s100, s101
	s_andn2_b64 vcc, exec, s[2:3]
	s_mov_b32 s4, s68
	s_mov_b32 s38, s82
	s_mov_b64 s[2:3], s[72:73]
	s_mov_b64 s[74:75], s[88:89]
	s_mov_b32 s89, 0x18000
	s_mov_b32 s88, 0x91a2b3c5
	s_cbranch_vccz .LBB0_652
.LBB0_623:
	s_add_i32 s64, s64, 1
	v_readlane_b32 s8, v246, 8
	s_mul_i32 s8, s64, s8
	s_mul_hi_u32 s9, s64, s48
	s_add_i32 s9, s9, s8
	s_mul_i32 s8, s64, s48
	s_add_u32 s72, s8, s6
	s_addc_u32 s73, s9, s63
	s_mov_b32 s101, 15
	s_cmp_eq_u32 s64, 4
	s_cbranch_scc0 .Lq_abi_sd
	s_cmp_lt_u32 s6, 80
	s_cbranch_scc0 .Lq_abi_sd
	s_mul_i32 s101, s6, 0xccd
	s_lshr_b32 s101, s101, 16
	s_mul_i32 s32, s101, 20
	s_sub_u32 s72, s6, s32
	s_add_u32 s72, s72, 0x400
	s_mov_b32 s73, 0
	s_lshl_b32 s101, 1, s101
.Lq_abi_sd:
	v_cmp_gt_i64_e32 vcc, s[72:73], v[158:159]
	v_cmp_lt_i64_e64 s[36:37], s[72:73], v[156:157]
	s_cbranch_vccnz .LBB0_629
	s_ashr_i32 s8, s72, 31
	s_lshr_b32 s8, s8, 29
	s_add_i32 s8, s72, s8
	s_and_b32 s9, s8, -8
	s_sub_i32 s9, s72, s9
	s_cmp_gt_i32 s9, 3
	s_mov_b64 s[68:69], -1
	s_cbranch_scc0 .LBB0_626
	s_mul_i32 s14, s9, 0x82
	s_add_i32 s39, s14, 4
	s_mov_b64 s[68:69], 0

.LBB0_629:
	s_ashr_i32 s83, s82, 31
	s_lshl_b64 s[8:9], s[82:83], 20
	s_add_u32 s88, s7, s8
	s_addc_u32 s89, s18, s9
	s_and_b64 s[8:9], s[36:37], exec
	s_cselect_b32 s39, s89, s75
	s_cselect_b32 s65, s88, s74
	s_ashr_i32 s69, s68, 31
	s_lshl_b64 s[8:9], s[68:69], 20
	s_add_u32 s72, s19, s8
	s_addc_u32 s73, s20, s9
	s_and_b64 s[8:9], s[36:37], exec
	s_cselect_b32 s66, s73, s3
	s_cselect_b32 s69, s72, s2
	s_add_u32 s83, s2, 0x100
	s_addc_u32 s84, s3, 0
	s_add_u32 vcc_lo, s74, 0x80080
	v_mov_b32_e32 v0, 0
	s_addc_u32 vcc_hi, s75, 0
	s_mov_b32 s8, -2
	v_mov_b32_e32 v1, v0
	v_mov_b32_e32 v2, v0
	v_mov_b32_e32 v3, v0
	v_mov_b32_e32 v4, v0
	v_mov_b32_e32 v5, v0
	v_mov_b32_e32 v6, v0
	v_mov_b32_e32 v7, v0
	v_mov_b32_e32 v16, v0
	v_mov_b32_e32 v17, v0
	v_mov_b32_e32 v18, v0
	v_mov_b32_e32 v19, v0
	v_mov_b32_e32 v20, v0
	v_mov_b32_e32 v21, v0
	v_mov_b32_e32 v22, v0
	v_mov_b32_e32 v23, v0
	v_mov_b32_e32 v32, v0
	v_mov_b32_e32 v33, v0
	v_mov_b32_e32 v34, v0
	v_mov_b32_e32 v35, v0
	v_mov_b32_e32 v36, v0
	v_mov_b32_e32 v37, v0
	v_mov_b32_e32 v38, v0
	v_mov_b32_e32 v39, v0
	v_mov_b32_e32 v48, v0
	v_mov_b32_e32 v49, v0
	v_mov_b32_e32 v50, v0
	v_mov_b32_e32 v51, v0
	v_mov_b32_e32 v52, v0
	v_mov_b32_e32 v53, v0
	v_mov_b32_e32 v54, v0
	v_mov_b32_e32 v55, v0
	v_mov_b32_e32 v8, v0
	v_mov_b32_e32 v9, v0
	v_mov_b32_e32 v10, v0
	v_mov_b32_e32 v11, v0
	v_mov_b32_e32 v12, v0
	v_mov_b32_e32 v13, v0
	v_mov_b32_e32 v14, v0
	v_mov_b32_e32 v15, v0
	v_mov_b32_e32 v24, v0
	v_mov_b32_e32 v25, v0
	v_mov_b32_e32 v26, v0
	v_mov_b32_e32 v27, v0
	v_mov_b32_e32 v28, v0
	v_mov_b32_e32 v29, v0
	v_mov_b32_e32 v30, v0
	v_mov_b32_e32 v31, v0
	v_mov_b32_e32 v40, v0
	v_mov_b32_e32 v41, v0
	v_mov_b32_e32 v42, v0
	v_mov_b32_e32 v43, v0
	v_mov_b32_e32 v44, v0
	v_mov_b32_e32 v45, v0
	v_mov_b32_e32 v46, v0
	v_mov_b32_e32 v47, v0
	v_mov_b32_e32 v56, v0
	v_mov_b32_e32 v57, v0
	v_mov_b32_e32 v58, v0
	v_mov_b32_e32 v59, v0
	v_mov_b32_e32 v60, v0
	v_mov_b32_e32 v61, v0
	v_mov_b32_e32 v62, v0
	v_mov_b32_e32 v63, v0
	v_mov_b32_e32 v64, v0
	v_mov_b32_e32 v65, v0
	v_mov_b32_e32 v66, v0
	v_mov_b32_e32 v67, v0
	v_mov_b32_e32 v68, v0
	v_mov_b32_e32 v69, v0
	v_mov_b32_e32 v70, v0
	v_mov_b32_e32 v71, v0
	v_mov_b32_e32 v80, v0
	v_mov_b32_e32 v81, v0
	v_mov_b32_e32 v82, v0
	v_mov_b32_e32 v83, v0
	v_mov_b32_e32 v84, v0
	v_mov_b32_e32 v85, v0
	v_mov_b32_e32 v86, v0
	v_mov_b32_e32 v87, v0
	v_mov_b32_e32 v96, v0
	v_mov_b32_e32 v97, v0
	v_mov_b32_e32 v98, v0
	v_mov_b32_e32 v99, v0
	v_mov_b32_e32 v100, v0
	v_mov_b32_e32 v101, v0
	v_mov_b32_e32 v102, v0
	v_mov_b32_e32 v103, v0
	v_mov_b32_e32 v112, v0
	v_mov_b32_e32 v113, v0
	v_mov_b32_e32 v114, v0
	v_mov_b32_e32 v115, v0
	v_mov_b32_e32 v116, v0
	v_mov_b32_e32 v117, v0
	v_mov_b32_e32 v118, v0
	v_mov_b32_e32 v119, v0
	v_mov_b32_e32 v72, v0
	v_mov_b32_e32 v73, v0
	v_mov_b32_e32 v74, v0
	v_mov_b32_e32 v75, v0
	v_mov_b32_e32 v76, v0
	v_mov_b32_e32 v77, v0
	v_mov_b32_e32 v78, v0
	v_mov_b32_e32 v79, v0
	v_mov_b32_e32 v88, v0
	v_mov_b32_e32 v89, v0
	v_mov_b32_e32 v90, v0
	v_mov_b32_e32 v91, v0
	v_mov_b32_e32 v92, v0
	v_mov_b32_e32 v93, v0
	v_mov_b32_e32 v94, v0
	v_mov_b32_e32 v95, v0
	v_mov_b32_e32 v104, v0
	v_mov_b32_e32 v105, v0
	v_mov_b32_e32 v106, v0
	v_mov_b32_e32 v107, v0
	v_mov_b32_e32 v108, v0
	v_mov_b32_e32 v109, v0
	v_mov_b32_e32 v110, v0
	v_mov_b32_e32 v111, v0
	v_mov_b32_e32 v120, v0
	v_mov_b32_e32 v121, v0
	v_mov_b32_e32 v122, v0
	v_mov_b32_e32 v123, v0
	v_mov_b32_e32 v124, v0
	v_mov_b32_e32 v125, v0
	v_mov_b32_e32 v126, v0
	v_mov_b32_e32 v127, v0
	s_cmp_eq_u32 s100, 15
	s_cbranch_scc0 .Lq_abi_disp
.LBB0_630:
	s_add_u32 s2, vcc_lo, 0xfff80080
	s_addc_u32 s3, vcc_hi, -1
	s_add_i32 s9, 0, 0x10000
	s_cmp_eq_u32 s8, 28
	s_cselect_b32 s75, s39, s3
	s_cselect_b32 s74, s65, s2
	v_add_u32_e32 v142, s9, v160
	s_cselect_b32 s3, s66, s84
	s_cselect_b32 s2, s69, s83
	s_add_i32 s24, 0, 0x14000
	ds_read_b128 v[138:141], v142
	ds_read_b128 v[164:167], v142 offset:1024
	ds_read_b128 v[168:171], v142 offset:2048
	ds_read_b128 v[172:175], v142 offset:3072
	v_add_u32_e32 v142, s24, v160
	ds_read_b128 v[176:179], v142
	ds_read_b128 v[190:193], v142 offset:1024
	ds_read_b128 v[194:197], v142 offset:2048
	ds_read_b128 v[198:201], v142 offset:3072
	v_lshl_add_u64 v[234:235], vcc, 0, v[136:137]
	s_add_i32 m0, s5, 0xc000
	ds_read_b128 v[202:205], v162
	ds_read_b128 v[206:209], v162 offset:1024
	ds_read_b128 v[210:213], v162 offset:2048
	ds_read_b128 v[214:217], v162 offset:3072
	ds_read_b128 v[218:221], v162 offset:4096
	ds_read_b128 v[222:225], v162 offset:5120
	ds_read_b128 v[226:229], v162 offset:6144
	ds_read_b128 v[230:233], v162 offset:7168
	global_load_lds_dwordx4 v[234:235], off
	v_lshl_add_u64 v[234:235], vcc, 0, v[134:135]
	s_add_i32 m0, s5, 0xe000
	s_nop 0
	global_load_lds_dwordx4 v[234:235], off
	s_waitcnt vmcnt(8)
	s_waitcnt lgkmcnt(0)
	s_barrier
	s_setprio 1
	s_waitcnt lgkmcnt(0)
	v_mfma_f32_16x16x32_bf16 v[124:127], v[138:141], v[202:205], v[124:127]
	v_mfma_f32_16x16x32_bf16 v[120:123], v[168:171], v[202:205], v[120:123]
	v_mfma_f32_16x16x32_bf16 v[108:111], v[138:141], v[210:213], v[108:111]
	v_mfma_f32_16x16x32_bf16 v[104:107], v[168:171], v[210:213], v[104:107]
	v_mfma_f32_16x16x32_bf16 v[92:95], v[138:141], v[218:221], v[92:95]
	v_mfma_f32_16x16x32_bf16 v[88:91], v[168:171], v[218:221], v[88:91]
	v_mfma_f32_16x16x32_bf16 v[76:79], v[138:141], v[226:229], v[76:79]
	v_mfma_f32_16x16x32_bf16 v[72:75], v[168:171], v[226:229], v[72:75]
	v_mfma_f32_16x16x32_bf16 v[124:127], v[164:167], v[206:209], v[124:127]
	v_mfma_f32_16x16x32_bf16 v[120:123], v[172:175], v[206:209], v[120:123]
	v_mfma_f32_16x16x32_bf16 v[108:111], v[164:167], v[214:217], v[108:111]
	v_mfma_f32_16x16x32_bf16 v[104:107], v[172:175], v[214:217], v[104:107]
	v_mfma_f32_16x16x32_bf16 v[92:95], v[164:167], v[222:225], v[92:95]
	v_mfma_f32_16x16x32_bf16 v[88:91], v[172:175], v[222:225], v[88:91]
	v_mfma_f32_16x16x32_bf16 v[76:79], v[164:167], v[230:233], v[76:79]
	v_mfma_f32_16x16x32_bf16 v[72:75], v[172:175], v[230:233], v[72:75]
	s_setprio 0
	s_setprio 1
	v_mfma_f32_16x16x32_bf16 v[116:119], v[176:179], v[202:205], v[116:119]
	v_mfma_f32_16x16x32_bf16 v[112:115], v[194:197], v[202:205], v[112:115]
	v_mfma_f32_16x16x32_bf16 v[100:103], v[176:179], v[210:213], v[100:103]
	v_mfma_f32_16x16x32_bf16 v[96:99], v[194:197], v[210:213], v[96:99]
	v_mfma_f32_16x16x32_bf16 v[84:87], v[176:179], v[218:221], v[84:87]
	v_mfma_f32_16x16x32_bf16 v[80:83], v[194:197], v[218:221], v[80:83]
	v_mfma_f32_16x16x32_bf16 v[68:71], v[176:179], v[226:229], v[68:71]
	v_mfma_f32_16x16x32_bf16 v[64:67], v[194:197], v[226:229], v[64:67]
	v_mfma_f32_16x16x32_bf16 v[116:119], v[190:193], v[206:209], v[116:119]
	v_mfma_f32_16x16x32_bf16 v[112:115], v[198:201], v[206:209], v[112:115]
	v_mfma_f32_16x16x32_bf16 v[100:103], v[190:193], v[214:217], v[100:103]
	v_mfma_f32_16x16x32_bf16 v[96:99], v[198:201], v[214:217], v[96:99]
	v_mfma_f32_16x16x32_bf16 v[84:87], v[190:193], v[222:225], v[84:87]
	v_mfma_f32_16x16x32_bf16 v[80:83], v[198:201], v[222:225], v[80:83]
	v_mfma_f32_16x16x32_bf16 v[68:71], v[190:193], v[230:233], v[68:71]
	v_mfma_f32_16x16x32_bf16 v[64:67], v[198:201], v[230:233], v[64:67]
	s_setprio 0
	s_barrier
	s_add_i32 s9, s9, s21
	v_lshl_add_u64 v[234:235], s[2:3], 0, v[144:145]
	s_mov_b32 m0, s9
	ds_read_b128 v[202:205], v162 offset:16384
	ds_read_b128 v[206:209], v162 offset:17408
	ds_read_b128 v[210:213], v162 offset:18432
	ds_read_b128 v[214:217], v162 offset:19456
	ds_read_b128 v[218:221], v162 offset:20480
	ds_read_b128 v[222:225], v162 offset:21504
	ds_read_b128 v[226:229], v162 offset:22528
	ds_read_b128 v[230:233], v162 offset:23552
	global_load_lds_dwordx4 v[234:235], off
	s_add_i32 m0, s9, 0x2000
	s_add_u32 s14, s2, 0x80000
	v_lshl_add_u64 v[236:237], s[2:3], 0, v[132:133]
	s_addc_u32 s15, s3, 0
	s_add_i32 s9, s24, s21
	global_load_lds_dwordx4 v[236:237], off
	v_lshl_add_u64 v[238:239], s[14:15], 0, v[144:145]
	s_mov_b32 m0, s9
	v_lshl_add_u64 v[240:241], s[74:75], 0, v[130:131]
	global_load_lds_dwordx4 v[238:239], off
	v_lshl_add_u64 v[238:239], s[14:15], 0, v[132:133]
	s_add_i32 m0, s9, 0x2000
	s_nop 0
	global_load_lds_dwordx4 v[238:239], off
	v_lshl_add_u64 v[238:239], s[74:75], 0, v[128:129]
	s_mov_b32 m0, s5
	s_nop 0
	global_load_lds_dwordx4 v[238:239], off
	s_mov_b32 m0, s33
	s_nop 0
	global_load_lds_dwordx4 v[240:241], off
	s_waitcnt vmcnt(8)
	s_waitcnt lgkmcnt(0)
	s_barrier
	s_setprio 1
	s_waitcnt lgkmcnt(0)
	v_mfma_f32_16x16x32_bf16 v[60:63], v[138:141], v[202:205], v[60:63]
	v_mfma_f32_16x16x32_bf16 v[56:59], v[168:171], v[202:205], v[56:59]
	v_mfma_f32_16x16x32_bf16 v[44:47], v[138:141], v[210:213], v[44:47]
	v_mfma_f32_16x16x32_bf16 v[40:43], v[168:171], v[210:213], v[40:43]
	v_mfma_f32_16x16x32_bf16 v[28:31], v[138:141], v[218:221], v[28:31]
	v_mfma_f32_16x16x32_bf16 v[24:27], v[168:171], v[218:221], v[24:27]
	v_mfma_f32_16x16x32_bf16 v[12:15], v[138:141], v[226:229], v[12:15]
	v_mfma_f32_16x16x32_bf16 v[8:11], v[168:171], v[226:229], v[8:11]
	v_mfma_f32_16x16x32_bf16 v[60:63], v[164:167], v[206:209], v[60:63]
	v_mfma_f32_16x16x32_bf16 v[56:59], v[172:175], v[206:209], v[56:59]
	v_mfma_f32_16x16x32_bf16 v[44:47], v[164:167], v[214:217], v[44:47]
	v_mfma_f32_16x16x32_bf16 v[40:43], v[172:175], v[214:217], v[40:43]
	v_mfma_f32_16x16x32_bf16 v[28:31], v[164:167], v[222:225], v[28:31]
	v_mfma_f32_16x16x32_bf16 v[24:27], v[172:175], v[222:225], v[24:27]
	v_mfma_f32_16x16x32_bf16 v[12:15], v[164:167], v[230:233], v[12:15]
	v_mfma_f32_16x16x32_bf16 v[8:11], v[172:175], v[230:233], v[8:11]
	s_setprio 0
	s_setprio 1
	v_mfma_f32_16x16x32_bf16 v[52:55], v[176:179], v[202:205], v[52:55]
	v_mfma_f32_16x16x32_bf16 v[48:51], v[194:197], v[202:205], v[48:51]
	v_mfma_f32_16x16x32_bf16 v[36:39], v[176:179], v[210:213], v[36:39]
	v_mfma_f32_16x16x32_bf16 v[32:35], v[194:197], v[210:213], v[32:35]
	v_mfma_f32_16x16x32_bf16 v[20:23], v[176:179], v[218:221], v[20:23]
	v_mfma_f32_16x16x32_bf16 v[16:19], v[194:197], v[218:221], v[16:19]
	v_mfma_f32_16x16x32_bf16 v[4:7], v[176:179], v[226:229], v[4:7]
	v_mfma_f32_16x16x32_bf16 v[0:3], v[194:197], v[226:229], v[0:3]
	v_mfma_f32_16x16x32_bf16 v[52:55], v[190:193], v[206:209], v[52:55]
	v_mfma_f32_16x16x32_bf16 v[48:51], v[198:201], v[206:209], v[48:51]
	v_mfma_f32_16x16x32_bf16 v[36:39], v[190:193], v[214:217], v[36:39]
	v_mfma_f32_16x16x32_bf16 v[32:35], v[198:201], v[214:217], v[32:35]
	v_mfma_f32_16x16x32_bf16 v[20:23], v[190:193], v[222:225], v[20:23]
	v_mfma_f32_16x16x32_bf16 v[16:19], v[198:201], v[222:225], v[16:19]
	v_mfma_f32_16x16x32_bf16 v[4:7], v[190:193], v[230:233], v[4:7]
	v_mfma_f32_16x16x32_bf16 v[0:3], v[198:201], v[230:233], v[0:3]
	s_setprio 0
	s_barrier
	s_add_i32 s9, 0, 0x18000
	v_add_u32_e32 v142, s9, v160
	s_add_i32 s24, 0, 0x1c000
	ds_read_b128 v[138:141], v142
	ds_read_b128 v[164:167], v142 offset:1024
	ds_read_b128 v[168:171], v142 offset:2048
	ds_read_b128 v[172:175], v142 offset:3072
	v_add_u32_e32 v142, s24, v160
	ds_read_b128 v[176:179], v142
	ds_read_b128 v[190:193], v142 offset:1024
	ds_read_b128 v[194:197], v142 offset:2048
	ds_read_b128 v[198:201], v142 offset:3072
	s_add_u32 s14, s74, 0x80000
	s_addc_u32 s15, s75, 0
	s_mov_b32 m0, s49
	v_lshl_add_u64 v[242:243], s[14:15], 0, v[128:129]
	ds_read_b128 v[202:205], v162 offset:32768
	ds_read_b128 v[206:209], v162 offset:33792
	ds_read_b128 v[210:213], v162 offset:34816
	ds_read_b128 v[214:217], v162 offset:35840
	ds_read_b128 v[218:221], v162 offset:36864
	ds_read_b128 v[222:225], v162 offset:37888
	ds_read_b128 v[226:229], v162 offset:38912
	ds_read_b128 v[230:233], v162 offset:39936
	global_load_lds_dwordx4 v[242:243], off
	v_lshl_add_u64 v[242:243], s[14:15], 0, v[130:131]
	s_mov_b32 m0, s51
	s_nop 0
	global_load_lds_dwordx4 v[242:243], off
	s_waitcnt vmcnt(8)
	s_waitcnt lgkmcnt(0)
	s_barrier
	s_setprio 1
	s_waitcnt lgkmcnt(0)
	v_mfma_f32_16x16x32_bf16 v[124:127], v[138:141], v[202:205], v[124:127]
	v_mfma_f32_16x16x32_bf16 v[120:123], v[168:171], v[202:205], v[120:123]
	v_mfma_f32_16x16x32_bf16 v[108:111], v[138:141], v[210:213], v[108:111]
	v_mfma_f32_16x16x32_bf16 v[104:107], v[168:171], v[210:213], v[104:107]
	v_mfma_f32_16x16x32_bf16 v[92:95], v[138:141], v[218:221], v[92:95]
	v_mfma_f32_16x16x32_bf16 v[88:91], v[168:171], v[218:221], v[88:91]
	v_mfma_f32_16x16x32_bf16 v[76:79], v[138:141], v[226:229], v[76:79]
	v_mfma_f32_16x16x32_bf16 v[72:75], v[168:171], v[226:229], v[72:75]
	v_mfma_f32_16x16x32_bf16 v[124:127], v[164:167], v[206:209], v[124:127]
	v_mfma_f32_16x16x32_bf16 v[120:123], v[172:175], v[206:209], v[120:123]
	v_mfma_f32_16x16x32_bf16 v[108:111], v[164:167], v[214:217], v[108:111]
	v_mfma_f32_16x16x32_bf16 v[104:107], v[172:175], v[214:217], v[104:107]
	v_mfma_f32_16x16x32_bf16 v[92:95], v[164:167], v[222:225], v[92:95]
	v_mfma_f32_16x16x32_bf16 v[88:91], v[172:175], v[222:225], v[88:91]
	v_mfma_f32_16x16x32_bf16 v[76:79], v[164:167], v[230:233], v[76:79]
	v_mfma_f32_16x16x32_bf16 v[72:75], v[172:175], v[230:233], v[72:75]
	s_setprio 0
	s_setprio 1
	v_mfma_f32_16x16x32_bf16 v[116:119], v[176:179], v[202:205], v[116:119]
	v_mfma_f32_16x16x32_bf16 v[112:115], v[194:197], v[202:205], v[112:115]
	v_mfma_f32_16x16x32_bf16 v[100:103], v[176:179], v[210:213], v[100:103]
	v_mfma_f32_16x16x32_bf16 v[96:99], v[194:197], v[210:213], v[96:99]
	v_mfma_f32_16x16x32_bf16 v[84:87], v[176:179], v[218:221], v[84:87]
	v_mfma_f32_16x16x32_bf16 v[80:83], v[194:197], v[218:221], v[80:83]
	v_mfma_f32_16x16x32_bf16 v[68:71], v[176:179], v[226:229], v[68:71]
	v_mfma_f32_16x16x32_bf16 v[64:67], v[194:197], v[226:229], v[64:67]
	v_mfma_f32_16x16x32_bf16 v[116:119], v[190:193], v[206:209], v[116:119]
	v_mfma_f32_16x16x32_bf16 v[112:115], v[198:201], v[206:209], v[112:115]
	v_mfma_f32_16x16x32_bf16 v[100:103], v[190:193], v[214:217], v[100:103]
	v_mfma_f32_16x16x32_bf16 v[96:99], v[198:201], v[214:217], v[96:99]
	v_mfma_f32_16x16x32_bf16 v[84:87], v[190:193], v[222:225], v[84:87]
	v_mfma_f32_16x16x32_bf16 v[80:83], v[198:201], v[222:225], v[80:83]
	v_mfma_f32_16x16x32_bf16 v[68:71], v[190:193], v[230:233], v[68:71]
	v_mfma_f32_16x16x32_bf16 v[64:67], v[198:201], v[230:233], v[64:67]
	s_setprio 0
	s_barrier
	s_add_i32 s9, s9, s21
	v_lshl_add_u64 v[234:235], v[234:235], 0, s[94:95]
	s_mov_b32 m0, s9
	ds_read_b128 v[202:205], v162 offset:49152
	ds_read_b128 v[206:209], v162 offset:50176
	ds_read_b128 v[210:213], v162 offset:51200
	ds_read_b128 v[214:217], v162 offset:52224
	ds_read_b128 v[218:221], v162 offset:53248
	ds_read_b128 v[222:225], v162 offset:54272
	ds_read_b128 v[226:229], v162 offset:55296
	ds_read_b128 v[230:233], v162 offset:56320
	global_load_lds_dwordx4 v[234:235], off
	s_add_i32 m0, s9, 0x2000
	s_add_u32 s2, s2, 0x80080
	v_lshl_add_u64 v[234:235], v[236:237], 0, s[94:95]
	s_addc_u32 s3, s3, 0
	s_add_i32 s9, s24, s21
	global_load_lds_dwordx4 v[234:235], off
	v_lshl_add_u64 v[234:235], s[2:3], 0, v[144:145]
	s_mov_b32 m0, s9
	s_nop 0
	global_load_lds_dwordx4 v[234:235], off
	v_lshl_add_u64 v[234:235], s[2:3], 0, v[132:133]
	s_add_i32 m0, s9, 0x2000
	s_nop 0
	global_load_lds_dwordx4 v[234:235], off
	v_lshl_add_u64 v[234:235], v[238:239], 0, s[94:95]
	s_mov_b32 m0, s61
	s_nop 0
	global_load_lds_dwordx4 v[234:235], off
	v_lshl_add_u64 v[234:235], v[240:241], 0, s[94:95]
	s_mov_b32 m0, s62
	s_nop 0
	global_load_lds_dwordx4 v[234:235], off
	s_waitcnt vmcnt(8)
	s_waitcnt lgkmcnt(0)
	s_barrier
	s_setprio 1
	s_waitcnt lgkmcnt(0)
	v_mfma_f32_16x16x32_bf16 v[60:63], v[138:141], v[202:205], v[60:63]
	v_mfma_f32_16x16x32_bf16 v[56:59], v[168:171], v[202:205], v[56:59]
	v_mfma_f32_16x16x32_bf16 v[44:47], v[138:141], v[210:213], v[44:47]
	v_mfma_f32_16x16x32_bf16 v[40:43], v[168:171], v[210:213], v[40:43]
	v_mfma_f32_16x16x32_bf16 v[28:31], v[138:141], v[218:221], v[28:31]
	v_mfma_f32_16x16x32_bf16 v[24:27], v[168:171], v[218:221], v[24:27]
	v_mfma_f32_16x16x32_bf16 v[12:15], v[138:141], v[226:229], v[12:15]
	v_mfma_f32_16x16x32_bf16 v[8:11], v[168:171], v[226:229], v[8:11]
	v_mfma_f32_16x16x32_bf16 v[60:63], v[164:167], v[206:209], v[60:63]
	v_mfma_f32_16x16x32_bf16 v[56:59], v[172:175], v[206:209], v[56:59]
	v_mfma_f32_16x16x32_bf16 v[44:47], v[164:167], v[214:217], v[44:47]
	v_mfma_f32_16x16x32_bf16 v[40:43], v[172:175], v[214:217], v[40:43]
	v_mfma_f32_16x16x32_bf16 v[28:31], v[164:167], v[222:225], v[28:31]
	v_mfma_f32_16x16x32_bf16 v[24:27], v[172:175], v[222:225], v[24:27]
	v_mfma_f32_16x16x32_bf16 v[12:15], v[164:167], v[230:233], v[12:15]
	v_mfma_f32_16x16x32_bf16 v[8:11], v[172:175], v[230:233], v[8:11]
	s_setprio 0
	s_setprio 1
	v_mfma_f32_16x16x32_bf16 v[52:55], v[176:179], v[202:205], v[52:55]
	v_mfma_f32_16x16x32_bf16 v[48:51], v[194:197], v[202:205], v[48:51]
	v_mfma_f32_16x16x32_bf16 v[36:39], v[176:179], v[210:213], v[36:39]
	v_mfma_f32_16x16x32_bf16 v[32:35], v[194:197], v[210:213], v[32:35]
	v_mfma_f32_16x16x32_bf16 v[20:23], v[176:179], v[218:221], v[20:23]
	v_mfma_f32_16x16x32_bf16 v[16:19], v[194:197], v[218:221], v[16:19]
	v_mfma_f32_16x16x32_bf16 v[4:7], v[176:179], v[226:229], v[4:7]
	v_mfma_f32_16x16x32_bf16 v[0:3], v[194:197], v[226:229], v[0:3]
	v_mfma_f32_16x16x32_bf16 v[52:55], v[190:193], v[206:209], v[52:55]
	v_mfma_f32_16x16x32_bf16 v[48:51], v[198:201], v[206:209], v[48:51]
	v_mfma_f32_16x16x32_bf16 v[36:39], v[190:193], v[214:217], v[36:39]
	v_mfma_f32_16x16x32_bf16 v[32:35], v[198:201], v[214:217], v[32:35]
	v_mfma_f32_16x16x32_bf16 v[20:23], v[190:193], v[222:225], v[20:23]
	v_mfma_f32_16x16x32_bf16 v[16:19], v[198:201], v[222:225], v[16:19]
	v_mfma_f32_16x16x32_bf16 v[4:7], v[190:193], v[230:233], v[4:7]
	v_mfma_f32_16x16x32_bf16 v[0:3], v[198:201], v[230:233], v[0:3]
	s_setprio 0
	s_barrier
	s_add_i32 s8, s8, 2
	s_add_u32 s83, s83, 0x100
	s_addc_u32 s84, s84, 0
	s_add_u32 vcc_lo, vcc_lo, 0x100
	s_addc_u32 vcc_hi, vcc_hi, 0
	s_cmp_gt_u32 s8, 29
	s_cbranch_scc0 .LBB0_630
	s_branch .Lq_abi_exit

.Lq_abi_0_loop:
	s_add_u32 s2, vcc_lo, 0xfff80080
	s_addc_u32 s3, vcc_hi, -1
	s_add_i32 s9, 0, 0x10000
	s_cmp_eq_u32 s8, 28
	s_cselect_b32 s75, s39, s3
	s_cselect_b32 s74, s65, s2
	v_add_u32_e32 v142, s9, v160
	s_cselect_b32 s3, s66, s84
	s_cselect_b32 s2, s69, s83
	s_add_i32 s24, 0, 0x14000
	ds_read_b128 v[138:141], v142
	ds_read_b128 v[164:167], v142 offset:1024
	ds_read_b128 v[168:171], v142 offset:2048
	ds_read_b128 v[172:175], v142 offset:3072
	v_add_u32_e32 v142, s24, v160
	v_lshl_add_u64 v[234:235], vcc, 0, v[136:137]
	s_add_i32 m0, s5, 0xc000
	ds_read_b128 v[202:205], v162
	ds_read_b128 v[206:209], v162 offset:1024
	ds_read_b128 v[210:213], v162 offset:2048
	ds_read_b128 v[214:217], v162 offset:3072
	ds_read_b128 v[218:221], v162 offset:4096
	ds_read_b128 v[222:225], v162 offset:5120
	ds_read_b128 v[226:229], v162 offset:6144
	ds_read_b128 v[230:233], v162 offset:7168
	v_lshl_add_u64 v[234:235], vcc, 0, v[134:135]
	s_add_i32 m0, s5, 0xe000
	s_nop 0
	s_waitcnt vmcnt(4)
	s_waitcnt lgkmcnt(0)
	s_barrier
	s_setprio 1
	s_waitcnt lgkmcnt(0)
	v_mfma_f32_16x16x32_bf16 v[124:127], v[138:141], v[202:205], v[124:127]
	v_mfma_f32_16x16x32_bf16 v[120:123], v[168:171], v[202:205], v[120:123]
	v_mfma_f32_16x16x32_bf16 v[108:111], v[138:141], v[210:213], v[108:111]
	v_mfma_f32_16x16x32_bf16 v[104:107], v[168:171], v[210:213], v[104:107]
	v_mfma_f32_16x16x32_bf16 v[92:95], v[138:141], v[218:221], v[92:95]
	v_mfma_f32_16x16x32_bf16 v[88:91], v[168:171], v[218:221], v[88:91]
	v_mfma_f32_16x16x32_bf16 v[76:79], v[138:141], v[226:229], v[76:79]
	v_mfma_f32_16x16x32_bf16 v[72:75], v[168:171], v[226:229], v[72:75]
	v_mfma_f32_16x16x32_bf16 v[124:127], v[164:167], v[206:209], v[124:127]
	v_mfma_f32_16x16x32_bf16 v[120:123], v[172:175], v[206:209], v[120:123]
	v_mfma_f32_16x16x32_bf16 v[108:111], v[164:167], v[214:217], v[108:111]
	v_mfma_f32_16x16x32_bf16 v[104:107], v[172:175], v[214:217], v[104:107]
	v_mfma_f32_16x16x32_bf16 v[92:95], v[164:167], v[222:225], v[92:95]
	v_mfma_f32_16x16x32_bf16 v[88:91], v[172:175], v[222:225], v[88:91]
	v_mfma_f32_16x16x32_bf16 v[76:79], v[164:167], v[230:233], v[76:79]
	v_mfma_f32_16x16x32_bf16 v[72:75], v[172:175], v[230:233], v[72:75]
	s_setprio 0
	s_setprio 1
	s_setprio 0
	s_barrier
	s_add_i32 s9, s9, s21
	v_lshl_add_u64 v[234:235], s[2:3], 0, v[144:145]
	s_mov_b32 m0, s9
	s_nop 0
	global_load_lds_dwordx4 v[234:235], off
	s_add_i32 m0, s9, 0x2000
	s_add_u32 s14, s2, 0x80000
	v_lshl_add_u64 v[236:237], s[2:3], 0, v[132:133]
	s_addc_u32 s15, s3, 0
	s_add_i32 s9, s24, s21
	global_load_lds_dwordx4 v[236:237], off
	v_lshl_add_u64 v[238:239], s[14:15], 0, v[144:145]
	s_mov_b32 m0, s9
	v_lshl_add_u64 v[240:241], s[74:75], 0, v[130:131]
	v_lshl_add_u64 v[238:239], s[14:15], 0, v[132:133]
	s_add_i32 m0, s9, 0x2000
	s_nop 0
	v_lshl_add_u64 v[238:239], s[74:75], 0, v[128:129]
	s_mov_b32 m0, s5
	s_nop 0
	global_load_lds_dwordx4 v[238:239], off
	s_mov_b32 m0, s33
	s_nop 0
	global_load_lds_dwordx4 v[240:241], off
	s_waitcnt vmcnt(4)
	s_waitcnt lgkmcnt(0)
	s_barrier
	s_setprio 1
	s_waitcnt lgkmcnt(0)
	s_setprio 0
	s_setprio 1
	s_setprio 0
	s_barrier
	s_add_i32 s9, 0, 0x18000
	v_add_u32_e32 v142, s9, v160
	s_add_i32 s24, 0, 0x1c000
	ds_read_b128 v[138:141], v142
	ds_read_b128 v[164:167], v142 offset:1024
	ds_read_b128 v[168:171], v142 offset:2048
	ds_read_b128 v[172:175], v142 offset:3072
	v_add_u32_e32 v142, s24, v160
	s_add_u32 s14, s74, 0x80000
	s_addc_u32 s15, s75, 0
	s_mov_b32 m0, s49
	v_lshl_add_u64 v[242:243], s[14:15], 0, v[128:129]
	ds_read_b128 v[202:205], v162 offset:32768
	ds_read_b128 v[206:209], v162 offset:33792
	ds_read_b128 v[210:213], v162 offset:34816
	ds_read_b128 v[214:217], v162 offset:35840
	ds_read_b128 v[218:221], v162 offset:36864
	ds_read_b128 v[222:225], v162 offset:37888
	ds_read_b128 v[226:229], v162 offset:38912
	ds_read_b128 v[230:233], v162 offset:39936
	v_lshl_add_u64 v[242:243], s[14:15], 0, v[130:131]
	s_mov_b32 m0, s51
	s_nop 0
	s_waitcnt vmcnt(4)
	s_waitcnt lgkmcnt(0)
	s_barrier
	s_setprio 1
	s_waitcnt lgkmcnt(0)
	v_mfma_f32_16x16x32_bf16 v[124:127], v[138:141], v[202:205], v[124:127]
	v_mfma_f32_16x16x32_bf16 v[120:123], v[168:171], v[202:205], v[120:123]
	v_mfma_f32_16x16x32_bf16 v[108:111], v[138:141], v[210:213], v[108:111]
	v_mfma_f32_16x16x32_bf16 v[104:107], v[168:171], v[210:213], v[104:107]
	v_mfma_f32_16x16x32_bf16 v[92:95], v[138:141], v[218:221], v[92:95]
	v_mfma_f32_16x16x32_bf16 v[88:91], v[168:171], v[218:221], v[88:91]
	v_mfma_f32_16x16x32_bf16 v[76:79], v[138:141], v[226:229], v[76:79]
	v_mfma_f32_16x16x32_bf16 v[72:75], v[168:171], v[226:229], v[72:75]
	v_mfma_f32_16x16x32_bf16 v[124:127], v[164:167], v[206:209], v[124:127]
	v_mfma_f32_16x16x32_bf16 v[120:123], v[172:175], v[206:209], v[120:123]
	v_mfma_f32_16x16x32_bf16 v[108:111], v[164:167], v[214:217], v[108:111]
	v_mfma_f32_16x16x32_bf16 v[104:107], v[172:175], v[214:217], v[104:107]
	v_mfma_f32_16x16x32_bf16 v[92:95], v[164:167], v[222:225], v[92:95]
	v_mfma_f32_16x16x32_bf16 v[88:91], v[172:175], v[222:225], v[88:91]
	v_mfma_f32_16x16x32_bf16 v[76:79], v[164:167], v[230:233], v[76:79]
	v_mfma_f32_16x16x32_bf16 v[72:75], v[172:175], v[230:233], v[72:75]
	s_setprio 0
	s_setprio 1
	s_setprio 0
	s_barrier
	s_add_i32 s9, s9, s21
	v_lshl_add_u64 v[234:235], v[234:235], 0, s[94:95]
	s_mov_b32 m0, s9
	s_nop 0
	global_load_lds_dwordx4 v[234:235], off
	s_add_i32 m0, s9, 0x2000
	s_add_u32 s2, s2, 0x80080
	v_lshl_add_u64 v[234:235], v[236:237], 0, s[94:95]
	s_addc_u32 s3, s3, 0
	s_add_i32 s9, s24, s21
	global_load_lds_dwordx4 v[234:235], off
	v_lshl_add_u64 v[234:235], s[2:3], 0, v[144:145]
	s_mov_b32 m0, s9
	s_nop 0
	v_lshl_add_u64 v[234:235], s[2:3], 0, v[132:133]
	s_add_i32 m0, s9, 0x2000
	s_nop 0
	v_lshl_add_u64 v[234:235], v[238:239], 0, s[94:95]
	s_mov_b32 m0, s61
	s_nop 0
	global_load_lds_dwordx4 v[234:235], off
	v_lshl_add_u64 v[234:235], v[240:241], 0, s[94:95]
	s_mov_b32 m0, s62
	s_nop 0
	global_load_lds_dwordx4 v[234:235], off
	s_waitcnt vmcnt(4)
	s_waitcnt lgkmcnt(0)
	s_barrier
	s_setprio 1
	s_waitcnt lgkmcnt(0)
	s_setprio 0
	s_setprio 1
	s_setprio 0
	s_barrier
	s_add_i32 s8, s8, 2
	s_add_u32 s83, s83, 0x100
	s_addc_u32 s84, s84, 0
	s_add_u32 vcc_lo, vcc_lo, 0x100
	s_addc_u32 vcc_hi, vcc_hi, 0
	s_cmp_gt_u32 s8, 29
	s_cbranch_scc0 .Lq_abi_0_loop
	s_branch .Lq_abi_exit
.Lq_abi_1_loop:
	s_add_u32 s2, vcc_lo, 0xfff80080
	s_addc_u32 s3, vcc_hi, -1
	s_add_i32 s9, 0, 0x10000
	s_cmp_eq_u32 s8, 28
	s_cselect_b32 s75, s39, s3
	s_cselect_b32 s74, s65, s2
	v_add_u32_e32 v142, s9, v160
	s_cselect_b32 s3, s66, s84
	s_cselect_b32 s2, s69, s83
	s_add_i32 s24, 0, 0x14000
	v_add_u32_e32 v142, s24, v160
	ds_read_b128 v[176:179], v142
	ds_read_b128 v[190:193], v142 offset:1024
	ds_read_b128 v[194:197], v142 offset:2048
	ds_read_b128 v[198:201], v142 offset:3072
	v_lshl_add_u64 v[234:235], vcc, 0, v[136:137]
	s_add_i32 m0, s5, 0xc000
	ds_read_b128 v[202:205], v162
	ds_read_b128 v[206:209], v162 offset:1024
	ds_read_b128 v[210:213], v162 offset:2048
	ds_read_b128 v[214:217], v162 offset:3072
	ds_read_b128 v[218:221], v162 offset:4096
	ds_read_b128 v[222:225], v162 offset:5120
	ds_read_b128 v[226:229], v162 offset:6144
	ds_read_b128 v[230:233], v162 offset:7168
	v_lshl_add_u64 v[234:235], vcc, 0, v[134:135]
	s_add_i32 m0, s5, 0xe000
	s_nop 0
	s_waitcnt vmcnt(4)
	s_waitcnt lgkmcnt(0)
	s_barrier
	s_setprio 1
	s_waitcnt lgkmcnt(0)
	s_setprio 0
	s_setprio 1
	v_mfma_f32_16x16x32_bf16 v[116:119], v[176:179], v[202:205], v[116:119]
	v_mfma_f32_16x16x32_bf16 v[112:115], v[194:197], v[202:205], v[112:115]
	v_mfma_f32_16x16x32_bf16 v[100:103], v[176:179], v[210:213], v[100:103]
	v_mfma_f32_16x16x32_bf16 v[96:99], v[194:197], v[210:213], v[96:99]
	v_mfma_f32_16x16x32_bf16 v[84:87], v[176:179], v[218:221], v[84:87]
	v_mfma_f32_16x16x32_bf16 v[80:83], v[194:197], v[218:221], v[80:83]
	v_mfma_f32_16x16x32_bf16 v[68:71], v[176:179], v[226:229], v[68:71]
	v_mfma_f32_16x16x32_bf16 v[64:67], v[194:197], v[226:229], v[64:67]
	v_mfma_f32_16x16x32_bf16 v[116:119], v[190:193], v[206:209], v[116:119]
	v_mfma_f32_16x16x32_bf16 v[112:115], v[198:201], v[206:209], v[112:115]
	v_mfma_f32_16x16x32_bf16 v[100:103], v[190:193], v[214:217], v[100:103]
	v_mfma_f32_16x16x32_bf16 v[96:99], v[198:201], v[214:217], v[96:99]
	v_mfma_f32_16x16x32_bf16 v[84:87], v[190:193], v[222:225], v[84:87]
	v_mfma_f32_16x16x32_bf16 v[80:83], v[198:201], v[222:225], v[80:83]
	v_mfma_f32_16x16x32_bf16 v[68:71], v[190:193], v[230:233], v[68:71]
	v_mfma_f32_16x16x32_bf16 v[64:67], v[198:201], v[230:233], v[64:67]
	s_setprio 0
	s_barrier
	s_add_i32 s9, s9, s21
	v_lshl_add_u64 v[234:235], s[2:3], 0, v[144:145]
	s_mov_b32 m0, s9
	s_add_i32 m0, s9, 0x2000
	s_add_u32 s14, s2, 0x80000
	v_lshl_add_u64 v[236:237], s[2:3], 0, v[132:133]
	s_addc_u32 s15, s3, 0
	s_add_i32 s9, s24, s21
	v_lshl_add_u64 v[238:239], s[14:15], 0, v[144:145]
	s_mov_b32 m0, s9
	v_lshl_add_u64 v[240:241], s[74:75], 0, v[130:131]
	global_load_lds_dwordx4 v[238:239], off
	v_lshl_add_u64 v[238:239], s[14:15], 0, v[132:133]
	s_add_i32 m0, s9, 0x2000
	s_nop 0
	global_load_lds_dwordx4 v[238:239], off
	v_lshl_add_u64 v[238:239], s[74:75], 0, v[128:129]
	s_mov_b32 m0, s5
	s_nop 0
	global_load_lds_dwordx4 v[238:239], off
	s_mov_b32 m0, s33
	s_nop 0
	global_load_lds_dwordx4 v[240:241], off
	s_waitcnt vmcnt(4)
	s_waitcnt lgkmcnt(0)
	s_barrier
	s_setprio 1
	s_waitcnt lgkmcnt(0)
	s_setprio 0
	s_setprio 1
	s_setprio 0
	s_barrier
	s_add_i32 s9, 0, 0x18000
	v_add_u32_e32 v142, s9, v160
	s_add_i32 s24, 0, 0x1c000
	v_add_u32_e32 v142, s24, v160
	ds_read_b128 v[176:179], v142
	ds_read_b128 v[190:193], v142 offset:1024
	ds_read_b128 v[194:197], v142 offset:2048
	ds_read_b128 v[198:201], v142 offset:3072
	s_add_u32 s14, s74, 0x80000
	s_addc_u32 s15, s75, 0
	s_mov_b32 m0, s49
	v_lshl_add_u64 v[242:243], s[14:15], 0, v[128:129]
	ds_read_b128 v[202:205], v162 offset:32768
	ds_read_b128 v[206:209], v162 offset:33792
	ds_read_b128 v[210:213], v162 offset:34816
	ds_read_b128 v[214:217], v162 offset:35840
	ds_read_b128 v[218:221], v162 offset:36864
	ds_read_b128 v[222:225], v162 offset:37888
	ds_read_b128 v[226:229], v162 offset:38912
	ds_read_b128 v[230:233], v162 offset:39936
	v_lshl_add_u64 v[242:243], s[14:15], 0, v[130:131]
	s_mov_b32 m0, s51
	s_nop 0
	s_waitcnt vmcnt(4)
	s_waitcnt lgkmcnt(0)
	s_barrier
	s_setprio 1
	s_waitcnt lgkmcnt(0)
	s_setprio 0
	s_setprio 1
	v_mfma_f32_16x16x32_bf16 v[116:119], v[176:179], v[202:205], v[116:119]
	v_mfma_f32_16x16x32_bf16 v[112:115], v[194:197], v[202:205], v[112:115]
	v_mfma_f32_16x16x32_bf16 v[100:103], v[176:179], v[210:213], v[100:103]
	v_mfma_f32_16x16x32_bf16 v[96:99], v[194:197], v[210:213], v[96:99]
	v_mfma_f32_16x16x32_bf16 v[84:87], v[176:179], v[218:221], v[84:87]
	v_mfma_f32_16x16x32_bf16 v[80:83], v[194:197], v[218:221], v[80:83]
	v_mfma_f32_16x16x32_bf16 v[68:71], v[176:179], v[226:229], v[68:71]
	v_mfma_f32_16x16x32_bf16 v[64:67], v[194:197], v[226:229], v[64:67]
	v_mfma_f32_16x16x32_bf16 v[116:119], v[190:193], v[206:209], v[116:119]
	v_mfma_f32_16x16x32_bf16 v[112:115], v[198:201], v[206:209], v[112:115]
	v_mfma_f32_16x16x32_bf16 v[100:103], v[190:193], v[214:217], v[100:103]
	v_mfma_f32_16x16x32_bf16 v[96:99], v[198:201], v[214:217], v[96:99]
	v_mfma_f32_16x16x32_bf16 v[84:87], v[190:193], v[222:225], v[84:87]
	v_mfma_f32_16x16x32_bf16 v[80:83], v[198:201], v[222:225], v[80:83]
	v_mfma_f32_16x16x32_bf16 v[68:71], v[190:193], v[230:233], v[68:71]
	v_mfma_f32_16x16x32_bf16 v[64:67], v[198:201], v[230:233], v[64:67]
	s_setprio 0
	s_barrier
	s_add_i32 s9, s9, s21
	v_lshl_add_u64 v[234:235], v[234:235], 0, s[94:95]
	s_mov_b32 m0, s9
	s_add_i32 m0, s9, 0x2000
	s_add_u32 s2, s2, 0x80080
	v_lshl_add_u64 v[234:235], v[236:237], 0, s[94:95]
	s_addc_u32 s3, s3, 0
	s_add_i32 s9, s24, s21
	v_lshl_add_u64 v[234:235], s[2:3], 0, v[144:145]
	s_mov_b32 m0, s9
	s_nop 0
	global_load_lds_dwordx4 v[234:235], off
	v_lshl_add_u64 v[234:235], s[2:3], 0, v[132:133]
	s_add_i32 m0, s9, 0x2000
	s_nop 0
	global_load_lds_dwordx4 v[234:235], off
	v_lshl_add_u64 v[234:235], v[238:239], 0, s[94:95]
	s_mov_b32 m0, s61
	s_nop 0
	global_load_lds_dwordx4 v[234:235], off
	v_lshl_add_u64 v[234:235], v[240:241], 0, s[94:95]
	s_mov_b32 m0, s62
	s_nop 0
	global_load_lds_dwordx4 v[234:235], off
	s_waitcnt vmcnt(4)
	s_waitcnt lgkmcnt(0)
	s_barrier
	s_setprio 1
	s_waitcnt lgkmcnt(0)
	s_setprio 0
	s_setprio 1
	s_setprio 0
	s_barrier
	s_add_i32 s8, s8, 2
	s_add_u32 s83, s83, 0x100
	s_addc_u32 s84, s84, 0
	s_add_u32 vcc_lo, vcc_lo, 0x100
	s_addc_u32 vcc_hi, vcc_hi, 0
	s_cmp_gt_u32 s8, 29
	s_cbranch_scc0 .Lq_abi_1_loop
	s_branch .Lq_abi_exit
.Lq_abi_2_loop:
	s_add_u32 s2, vcc_lo, 0xfff80080
	s_addc_u32 s3, vcc_hi, -1
	s_add_i32 s9, 0, 0x10000
	s_cmp_eq_u32 s8, 28
	s_cselect_b32 s75, s39, s3
	s_cselect_b32 s74, s65, s2
	v_add_u32_e32 v142, s9, v160
	s_cselect_b32 s3, s66, s84
	s_cselect_b32 s2, s69, s83
	s_add_i32 s24, 0, 0x14000
	ds_read_b128 v[138:141], v142
	ds_read_b128 v[164:167], v142 offset:1024
	ds_read_b128 v[168:171], v142 offset:2048
	ds_read_b128 v[172:175], v142 offset:3072
	v_add_u32_e32 v142, s24, v160
	v_lshl_add_u64 v[234:235], vcc, 0, v[136:137]
	s_add_i32 m0, s5, 0xc000
	s_nop 0
	global_load_lds_dwordx4 v[234:235], off
	v_lshl_add_u64 v[234:235], vcc, 0, v[134:135]
	s_add_i32 m0, s5, 0xe000
	s_nop 0
	global_load_lds_dwordx4 v[234:235], off
	s_waitcnt vmcnt(4)
	s_waitcnt lgkmcnt(0)
	s_barrier
	s_setprio 1
	s_waitcnt lgkmcnt(0)
	s_setprio 0
	s_setprio 1
	s_setprio 0
	s_barrier
	s_add_i32 s9, s9, s21
	v_lshl_add_u64 v[234:235], s[2:3], 0, v[144:145]
	s_mov_b32 m0, s9
	ds_read_b128 v[202:205], v162 offset:16384
	ds_read_b128 v[206:209], v162 offset:17408
	ds_read_b128 v[210:213], v162 offset:18432
	ds_read_b128 v[214:217], v162 offset:19456
	ds_read_b128 v[218:221], v162 offset:20480
	ds_read_b128 v[222:225], v162 offset:21504
	ds_read_b128 v[226:229], v162 offset:22528
	ds_read_b128 v[230:233], v162 offset:23552
	global_load_lds_dwordx4 v[234:235], off
	s_add_i32 m0, s9, 0x2000
	s_add_u32 s14, s2, 0x80000
	v_lshl_add_u64 v[236:237], s[2:3], 0, v[132:133]
	s_addc_u32 s15, s3, 0
	s_add_i32 s9, s24, s21
	global_load_lds_dwordx4 v[236:237], off
	v_lshl_add_u64 v[238:239], s[14:15], 0, v[144:145]
	s_mov_b32 m0, s9
	v_lshl_add_u64 v[240:241], s[74:75], 0, v[130:131]
	v_lshl_add_u64 v[238:239], s[14:15], 0, v[132:133]
	s_add_i32 m0, s9, 0x2000
	s_nop 0
	v_lshl_add_u64 v[238:239], s[74:75], 0, v[128:129]
	s_mov_b32 m0, s5
	s_nop 0
	s_mov_b32 m0, s33
	s_nop 0
	s_waitcnt vmcnt(4)
	s_waitcnt lgkmcnt(0)
	s_barrier
	s_setprio 1
	s_waitcnt lgkmcnt(0)
	v_mfma_f32_16x16x32_bf16 v[60:63], v[138:141], v[202:205], v[60:63]
	v_mfma_f32_16x16x32_bf16 v[56:59], v[168:171], v[202:205], v[56:59]
	v_mfma_f32_16x16x32_bf16 v[44:47], v[138:141], v[210:213], v[44:47]
	v_mfma_f32_16x16x32_bf16 v[40:43], v[168:171], v[210:213], v[40:43]
	v_mfma_f32_16x16x32_bf16 v[28:31], v[138:141], v[218:221], v[28:31]
	v_mfma_f32_16x16x32_bf16 v[24:27], v[168:171], v[218:221], v[24:27]
	v_mfma_f32_16x16x32_bf16 v[12:15], v[138:141], v[226:229], v[12:15]
	v_mfma_f32_16x16x32_bf16 v[8:11], v[168:171], v[226:229], v[8:11]
	v_mfma_f32_16x16x32_bf16 v[60:63], v[164:167], v[206:209], v[60:63]
	v_mfma_f32_16x16x32_bf16 v[56:59], v[172:175], v[206:209], v[56:59]
	v_mfma_f32_16x16x32_bf16 v[44:47], v[164:167], v[214:217], v[44:47]
	v_mfma_f32_16x16x32_bf16 v[40:43], v[172:175], v[214:217], v[40:43]
	v_mfma_f32_16x16x32_bf16 v[28:31], v[164:167], v[222:225], v[28:31]
	v_mfma_f32_16x16x32_bf16 v[24:27], v[172:175], v[222:225], v[24:27]
	v_mfma_f32_16x16x32_bf16 v[12:15], v[164:167], v[230:233], v[12:15]
	v_mfma_f32_16x16x32_bf16 v[8:11], v[172:175], v[230:233], v[8:11]
	s_setprio 0
	s_setprio 1
	s_setprio 0
	s_barrier
	s_add_i32 s9, 0, 0x18000
	v_add_u32_e32 v142, s9, v160
	s_add_i32 s24, 0, 0x1c000
	ds_read_b128 v[138:141], v142
	ds_read_b128 v[164:167], v142 offset:1024
	ds_read_b128 v[168:171], v142 offset:2048
	ds_read_b128 v[172:175], v142 offset:3072
	v_add_u32_e32 v142, s24, v160
	s_add_u32 s14, s74, 0x80000
	s_addc_u32 s15, s75, 0
	s_mov_b32 m0, s49
	v_lshl_add_u64 v[242:243], s[14:15], 0, v[128:129]
	global_load_lds_dwordx4 v[242:243], off
	v_lshl_add_u64 v[242:243], s[14:15], 0, v[130:131]
	s_mov_b32 m0, s51
	s_nop 0
	global_load_lds_dwordx4 v[242:243], off
	s_waitcnt vmcnt(4)
	s_waitcnt lgkmcnt(0)
	s_barrier
	s_setprio 1
	s_waitcnt lgkmcnt(0)
	s_setprio 0
	s_setprio 1
	s_setprio 0
	s_barrier
	s_add_i32 s9, s9, s21
	v_lshl_add_u64 v[234:235], v[234:235], 0, s[94:95]
	s_mov_b32 m0, s9
	ds_read_b128 v[202:205], v162 offset:49152
	ds_read_b128 v[206:209], v162 offset:50176
	ds_read_b128 v[210:213], v162 offset:51200
	ds_read_b128 v[214:217], v162 offset:52224
	ds_read_b128 v[218:221], v162 offset:53248
	ds_read_b128 v[222:225], v162 offset:54272
	ds_read_b128 v[226:229], v162 offset:55296
	ds_read_b128 v[230:233], v162 offset:56320
	global_load_lds_dwordx4 v[234:235], off
	s_add_i32 m0, s9, 0x2000
	s_add_u32 s2, s2, 0x80080
	v_lshl_add_u64 v[234:235], v[236:237], 0, s[94:95]
	s_addc_u32 s3, s3, 0
	s_add_i32 s9, s24, s21
	global_load_lds_dwordx4 v[234:235], off
	v_lshl_add_u64 v[234:235], s[2:3], 0, v[144:145]
	s_mov_b32 m0, s9
	s_nop 0
	v_lshl_add_u64 v[234:235], s[2:3], 0, v[132:133]
	s_add_i32 m0, s9, 0x2000
	s_nop 0
	v_lshl_add_u64 v[234:235], v[238:239], 0, s[94:95]
	s_mov_b32 m0, s61
	s_nop 0
	v_lshl_add_u64 v[234:235], v[240:241], 0, s[94:95]
	s_mov_b32 m0, s62
	s_nop 0
	s_waitcnt vmcnt(4)
	s_waitcnt lgkmcnt(0)
	s_barrier
	s_setprio 1
	s_waitcnt lgkmcnt(0)
	v_mfma_f32_16x16x32_bf16 v[60:63], v[138:141], v[202:205], v[60:63]
	v_mfma_f32_16x16x32_bf16 v[56:59], v[168:171], v[202:205], v[56:59]
	v_mfma_f32_16x16x32_bf16 v[44:47], v[138:141], v[210:213], v[44:47]
	v_mfma_f32_16x16x32_bf16 v[40:43], v[168:171], v[210:213], v[40:43]
	v_mfma_f32_16x16x32_bf16 v[28:31], v[138:141], v[218:221], v[28:31]
	v_mfma_f32_16x16x32_bf16 v[24:27], v[168:171], v[218:221], v[24:27]
	v_mfma_f32_16x16x32_bf16 v[12:15], v[138:141], v[226:229], v[12:15]
	v_mfma_f32_16x16x32_bf16 v[8:11], v[168:171], v[226:229], v[8:11]
	v_mfma_f32_16x16x32_bf16 v[60:63], v[164:167], v[206:209], v[60:63]
	v_mfma_f32_16x16x32_bf16 v[56:59], v[172:175], v[206:209], v[56:59]
	v_mfma_f32_16x16x32_bf16 v[44:47], v[164:167], v[214:217], v[44:47]
	v_mfma_f32_16x16x32_bf16 v[40:43], v[172:175], v[214:217], v[40:43]
	v_mfma_f32_16x16x32_bf16 v[28:31], v[164:167], v[222:225], v[28:31]
	v_mfma_f32_16x16x32_bf16 v[24:27], v[172:175], v[222:225], v[24:27]
	v_mfma_f32_16x16x32_bf16 v[12:15], v[164:167], v[230:233], v[12:15]
	v_mfma_f32_16x16x32_bf16 v[8:11], v[172:175], v[230:233], v[8:11]
	s_setprio 0
	s_setprio 1
	s_setprio 0
	s_barrier
	s_add_i32 s8, s8, 2
	s_add_u32 s83, s83, 0x100
	s_addc_u32 s84, s84, 0
	s_add_u32 vcc_lo, vcc_lo, 0x100
	s_addc_u32 vcc_hi, vcc_hi, 0
	s_cmp_gt_u32 s8, 29
	s_cbranch_scc0 .Lq_abi_2_loop
	s_branch .Lq_abi_exit
.Lq_abi_3_loop:
	s_add_u32 s2, vcc_lo, 0xfff80080
	s_addc_u32 s3, vcc_hi, -1
	s_add_i32 s9, 0, 0x10000
	s_cmp_eq_u32 s8, 28
	s_cselect_b32 s75, s39, s3
	s_cselect_b32 s74, s65, s2
	v_add_u32_e32 v142, s9, v160
	s_cselect_b32 s3, s66, s84
	s_cselect_b32 s2, s69, s83
	s_add_i32 s24, 0, 0x14000
	v_add_u32_e32 v142, s24, v160
	ds_read_b128 v[176:179], v142
	ds_read_b128 v[190:193], v142 offset:1024
	ds_read_b128 v[194:197], v142 offset:2048
	ds_read_b128 v[198:201], v142 offset:3072
	v_lshl_add_u64 v[234:235], vcc, 0, v[136:137]
	s_add_i32 m0, s5, 0xc000
	s_nop 0
	global_load_lds_dwordx4 v[234:235], off
	v_lshl_add_u64 v[234:235], vcc, 0, v[134:135]
	s_add_i32 m0, s5, 0xe000
	s_nop 0
	global_load_lds_dwordx4 v[234:235], off
	s_waitcnt vmcnt(4)
	s_waitcnt lgkmcnt(0)
	s_barrier
	s_setprio 1
	s_waitcnt lgkmcnt(0)
	s_setprio 0
	s_setprio 1
	s_setprio 0
	s_barrier
	s_add_i32 s9, s9, s21
	v_lshl_add_u64 v[234:235], s[2:3], 0, v[144:145]
	s_mov_b32 m0, s9
	ds_read_b128 v[202:205], v162 offset:16384
	ds_read_b128 v[206:209], v162 offset:17408
	ds_read_b128 v[210:213], v162 offset:18432
	ds_read_b128 v[214:217], v162 offset:19456
	ds_read_b128 v[218:221], v162 offset:20480
	ds_read_b128 v[222:225], v162 offset:21504
	ds_read_b128 v[226:229], v162 offset:22528
	ds_read_b128 v[230:233], v162 offset:23552
	s_add_i32 m0, s9, 0x2000
	s_add_u32 s14, s2, 0x80000
	v_lshl_add_u64 v[236:237], s[2:3], 0, v[132:133]
	s_addc_u32 s15, s3, 0
	s_add_i32 s9, s24, s21
	v_lshl_add_u64 v[238:239], s[14:15], 0, v[144:145]
	s_mov_b32 m0, s9
	v_lshl_add_u64 v[240:241], s[74:75], 0, v[130:131]
	global_load_lds_dwordx4 v[238:239], off
	v_lshl_add_u64 v[238:239], s[14:15], 0, v[132:133]
	s_add_i32 m0, s9, 0x2000
	s_nop 0
	global_load_lds_dwordx4 v[238:239], off
	v_lshl_add_u64 v[238:239], s[74:75], 0, v[128:129]
	s_mov_b32 m0, s5
	s_nop 0
	s_mov_b32 m0, s33
	s_nop 0
	s_waitcnt vmcnt(4)
	s_waitcnt lgkmcnt(0)
	s_barrier
	s_setprio 1
	s_waitcnt lgkmcnt(0)
	s_setprio 0
	s_setprio 1
	v_mfma_f32_16x16x32_bf16 v[52:55], v[176:179], v[202:205], v[52:55]
	v_mfma_f32_16x16x32_bf16 v[48:51], v[194:197], v[202:205], v[48:51]
	v_mfma_f32_16x16x32_bf16 v[36:39], v[176:179], v[210:213], v[36:39]
	v_mfma_f32_16x16x32_bf16 v[32:35], v[194:197], v[210:213], v[32:35]
	v_mfma_f32_16x16x32_bf16 v[20:23], v[176:179], v[218:221], v[20:23]
	v_mfma_f32_16x16x32_bf16 v[16:19], v[194:197], v[218:221], v[16:19]
	v_mfma_f32_16x16x32_bf16 v[4:7], v[176:179], v[226:229], v[4:7]
	v_mfma_f32_16x16x32_bf16 v[0:3], v[194:197], v[226:229], v[0:3]
	v_mfma_f32_16x16x32_bf16 v[52:55], v[190:193], v[206:209], v[52:55]
	v_mfma_f32_16x16x32_bf16 v[48:51], v[198:201], v[206:209], v[48:51]
	v_mfma_f32_16x16x32_bf16 v[36:39], v[190:193], v[214:217], v[36:39]
	v_mfma_f32_16x16x32_bf16 v[32:35], v[198:201], v[214:217], v[32:35]
	v_mfma_f32_16x16x32_bf16 v[20:23], v[190:193], v[222:225], v[20:23]
	v_mfma_f32_16x16x32_bf16 v[16:19], v[198:201], v[222:225], v[16:19]
	v_mfma_f32_16x16x32_bf16 v[4:7], v[190:193], v[230:233], v[4:7]
	v_mfma_f32_16x16x32_bf16 v[0:3], v[198:201], v[230:233], v[0:3]
	s_setprio 0
	s_barrier
	s_add_i32 s9, 0, 0x18000
	v_add_u32_e32 v142, s9, v160
	s_add_i32 s24, 0, 0x1c000
	v_add_u32_e32 v142, s24, v160
	ds_read_b128 v[176:179], v142
	ds_read_b128 v[190:193], v142 offset:1024
	ds_read_b128 v[194:197], v142 offset:2048
	ds_read_b128 v[198:201], v142 offset:3072
	s_add_u32 s14, s74, 0x80000
	s_addc_u32 s15, s75, 0
	s_mov_b32 m0, s49
	v_lshl_add_u64 v[242:243], s[14:15], 0, v[128:129]
	global_load_lds_dwordx4 v[242:243], off
	v_lshl_add_u64 v[242:243], s[14:15], 0, v[130:131]
	s_mov_b32 m0, s51
	s_nop 0
	global_load_lds_dwordx4 v[242:243], off
	s_waitcnt vmcnt(4)
	s_waitcnt lgkmcnt(0)
	s_barrier
	s_setprio 1
	s_waitcnt lgkmcnt(0)
	s_setprio 0
	s_setprio 1
	s_setprio 0
	s_barrier
	s_add_i32 s9, s9, s21
	v_lshl_add_u64 v[234:235], v[234:235], 0, s[94:95]
	s_mov_b32 m0, s9
	ds_read_b128 v[202:205], v162 offset:49152
	ds_read_b128 v[206:209], v162 offset:50176
	ds_read_b128 v[210:213], v162 offset:51200
	ds_read_b128 v[214:217], v162 offset:52224
	ds_read_b128 v[218:221], v162 offset:53248
	ds_read_b128 v[222:225], v162 offset:54272
	ds_read_b128 v[226:229], v162 offset:55296
	ds_read_b128 v[230:233], v162 offset:56320
	s_add_i32 m0, s9, 0x2000
	s_add_u32 s2, s2, 0x80080
	v_lshl_add_u64 v[234:235], v[236:237], 0, s[94:95]
	s_addc_u32 s3, s3, 0
	s_add_i32 s9, s24, s21
	v_lshl_add_u64 v[234:235], s[2:3], 0, v[144:145]
	s_mov_b32 m0, s9
	s_nop 0
	global_load_lds_dwordx4 v[234:235], off
	v_lshl_add_u64 v[234:235], s[2:3], 0, v[132:133]
	s_add_i32 m0, s9, 0x2000
	s_nop 0
	global_load_lds_dwordx4 v[234:235], off
	v_lshl_add_u64 v[234:235], v[238:239], 0, s[94:95]
	s_mov_b32 m0, s61
	s_nop 0
	v_lshl_add_u64 v[234:235], v[240:241], 0, s[94:95]
	s_mov_b32 m0, s62
	s_nop 0
	s_waitcnt vmcnt(4)
	s_waitcnt lgkmcnt(0)
	s_barrier
	s_setprio 1
	s_waitcnt lgkmcnt(0)
	s_setprio 0
	s_setprio 1
	v_mfma_f32_16x16x32_bf16 v[52:55], v[176:179], v[202:205], v[52:55]
	v_mfma_f32_16x16x32_bf16 v[48:51], v[194:197], v[202:205], v[48:51]
	v_mfma_f32_16x16x32_bf16 v[36:39], v[176:179], v[210:213], v[36:39]
	v_mfma_f32_16x16x32_bf16 v[32:35], v[194:197], v[210:213], v[32:35]
	v_mfma_f32_16x16x32_bf16 v[20:23], v[176:179], v[218:221], v[20:23]
	v_mfma_f32_16x16x32_bf16 v[16:19], v[194:197], v[218:221], v[16:19]
	v_mfma_f32_16x16x32_bf16 v[4:7], v[176:179], v[226:229], v[4:7]
	v_mfma_f32_16x16x32_bf16 v[0:3], v[194:197], v[226:229], v[0:3]
	v_mfma_f32_16x16x32_bf16 v[52:55], v[190:193], v[206:209], v[52:55]
	v_mfma_f32_16x16x32_bf16 v[48:51], v[198:201], v[206:209], v[48:51]
	v_mfma_f32_16x16x32_bf16 v[36:39], v[190:193], v[214:217], v[36:39]
	v_mfma_f32_16x16x32_bf16 v[32:35], v[198:201], v[214:217], v[32:35]
	v_mfma_f32_16x16x32_bf16 v[20:23], v[190:193], v[222:225], v[20:23]
	v_mfma_f32_16x16x32_bf16 v[16:19], v[198:201], v[222:225], v[16:19]
	v_mfma_f32_16x16x32_bf16 v[4:7], v[190:193], v[230:233], v[4:7]
	v_mfma_f32_16x16x32_bf16 v[0:3], v[198:201], v[230:233], v[0:3]
	s_setprio 0
	s_barrier
	s_add_i32 s8, s8, 2
	s_add_u32 s83, s83, 0x100
	s_addc_u32 s84, s84, 0
	s_add_u32 vcc_lo, vcc_lo, 0x100
	s_addc_u32 vcc_hi, vcc_hi, 0
	s_cmp_gt_u32 s8, 29
	s_cbranch_scc0 .Lq_abi_3_loop
	s_branch .Lq_abi_exit
.Lq_abi_exit:
	s_and_b64 vcc, exec, s[52:53]
	s_cbranch_vccz .LBB0_633
	s_barrier

.LBB0_635:
	v_lshl_or_b32 v140, s4, 8, v161
	v_mov_b64_e32 v[164:165], s[30:31]
	v_ashrrev_i32_e32 v141, 31, v140
	v_mad_i64_i32 v[164:165], s[2:3], v138, s86, v[164:165]
	v_lshl_add_u64 v[164:165], v[140:141], 1, v[164:165]
	v_pk_mul_f32 v[126:127], v[126:127], v[146:147] op_sel_hi:[1,0]
	v_pk_mul_f32 v[124:125], v[124:125], v[146:147] op_sel_hi:[1,0]
	v_pk_mul_f32 v[166:167], v[122:123], v[146:147] op_sel_hi:[1,0]
	v_pk_mul_f32 v[122:123], v[120:121], v[146:147] op_sel_hi:[1,0]
	v_cvt_pk_bf16_f32 v120, v124, v125
	v_cvt_pk_bf16_f32 v121, v126, v127
	v_pk_mul_f32 v[116:117], v[116:117], v[146:147] op_sel_hi:[1,0]
	v_cvt_pk_bf16_f32 v122, v122, v123
	v_cvt_pk_bf16_f32 v123, v166, v167
	s_bitcmp1_b32 s100, 0
	s_cbranch_scc0 .Lq_abi_e0
	flat_store_dwordx4 v[164:165], v[120:123]
.Lq_abi_e0:
	v_pk_mul_f32 v[118:119], v[118:119], v[146:147] op_sel_hi:[1,0]
	s_and_b64 vcc, exec, s[38:39]
	v_pk_mul_f32 v[120:121], v[114:115], v[146:147] op_sel_hi:[1,0]
	v_pk_mul_f32 v[114:115], v[112:113], v[146:147] op_sel_hi:[1,0]
	v_cvt_pk_bf16_f32 v112, v116, v117
	v_cvt_pk_bf16_f32 v113, v118, v119
	s_nop 0
	v_cvt_pk_bf16_f32 v114, v114, v115
	v_cvt_pk_bf16_f32 v115, v120, v121
	s_bitcmp1_b32 s100, 1
	s_cbranch_scc0 .Lq_abi_e1
	flat_store_dwordx4 v[164:165], v[112:115] offset:256
.Lq_abi_e1:
	s_nop 1
	v_or_b32_e32 v112, 16, v138
	v_ashrrev_i32_e32 v113, 31, v112
	s_cbranch_vccnz .LBB0_637
	v_lshl_add_u64 v[114:115], v[112:113], 2, s[40:41]
	s_nop 1
	v_mov_b32_e32 v113, v201
	v_fmamk_f32 v113, v113, 0x3a000000, v181
	v_mul_f32_e32 v114, 0x4b800000, v113
	v_cmp_gt_f32_e32 vcc, s80, v113
	s_nop 1
	v_cndmask_b32_e32 v113, v113, v114, vcc
	v_rsq_f32_e32 v113, v113
	s_nop 0
	v_mul_f32_e32 v114, 0x45800000, v113
	v_cndmask_b32_e32 v142, v113, v114, vcc
.LBB0_637:
	v_mov_b64_e32 v[114:115], s[30:31]
	v_mad_i64_i32 v[112:113], s[2:3], v112, s86, v[114:115]
	v_lshl_add_u64 v[112:113], v[140:141], 1, v[112:113]
	v_pk_mul_f32 v[110:111], v[110:111], v[142:143] op_sel_hi:[1,0]
	v_pk_mul_f32 v[108:109], v[108:109], v[142:143] op_sel_hi:[1,0]
	v_pk_mul_f32 v[114:115], v[106:107], v[142:143] op_sel_hi:[1,0]
	v_pk_mul_f32 v[106:107], v[104:105], v[142:143] op_sel_hi:[1,0]
	v_cvt_pk_bf16_f32 v104, v108, v109
	v_cvt_pk_bf16_f32 v105, v110, v111
	v_pk_mul_f32 v[100:101], v[100:101], v[142:143] op_sel_hi:[1,0]
	v_cvt_pk_bf16_f32 v106, v106, v107
	v_cvt_pk_bf16_f32 v107, v114, v115
	s_bitcmp1_b32 s100, 0
	s_cbranch_scc0 .Lq_abi_e2
	flat_store_dwordx4 v[112:113], v[104:107]
.Lq_abi_e2:
	v_pk_mul_f32 v[102:103], v[102:103], v[142:143] op_sel_hi:[1,0]
	s_and_b64 vcc, exec, s[38:39]
	v_pk_mul_f32 v[104:105], v[98:99], v[142:143] op_sel_hi:[1,0]
	v_pk_mul_f32 v[98:99], v[96:97], v[142:143] op_sel_hi:[1,0]
	v_cvt_pk_bf16_f32 v96, v100, v101
	v_cvt_pk_bf16_f32 v97, v102, v103
	v_or_b32_e32 v100, 32, v138
	v_cvt_pk_bf16_f32 v98, v98, v99
	v_cvt_pk_bf16_f32 v99, v104, v105
	s_bitcmp1_b32 s100, 1
	s_cbranch_scc0 .Lq_abi_e3
	flat_store_dwordx4 v[112:113], v[96:99] offset:256
.Lq_abi_e3:
	v_ashrrev_i32_e32 v101, 31, v100
	s_nop 0
	v_mov_b32_e32 v96, 1.0
	v_mov_b32_e32 v98, 1.0
	s_cbranch_vccnz .LBB0_639
	v_lshl_add_u64 v[98:99], v[100:101], 2, s[40:41]
	s_nop 1
	v_mov_b32_e32 v97, v202
	v_fmamk_f32 v97, v97, 0x3a000000, v181
	v_mul_f32_e32 v98, 0x4b800000, v97
	v_cmp_gt_f32_e32 vcc, s80, v97
	s_nop 1
	v_cndmask_b32_e32 v97, v97, v98, vcc
	v_rsq_f32_e32 v97, v97
	s_nop 0
	v_mul_f32_e32 v98, 0x45800000, v97
	v_cndmask_b32_e32 v98, v97, v98, vcc
.LBB0_639:
	v_mov_b64_e32 v[102:103], s[30:31]
	v_mad_i64_i32 v[100:101], s[2:3], v100, s86, v[102:103]
	v_lshl_add_u64 v[100:101], v[140:141], 1, v[100:101]
	v_pk_mul_f32 v[94:95], v[94:95], v[98:99] op_sel_hi:[1,0]
	v_pk_mul_f32 v[92:93], v[92:93], v[98:99] op_sel_hi:[1,0]
	v_pk_mul_f32 v[102:103], v[90:91], v[98:99] op_sel_hi:[1,0]
	v_pk_mul_f32 v[90:91], v[88:89], v[98:99] op_sel_hi:[1,0]
	v_cvt_pk_bf16_f32 v88, v92, v93
	v_cvt_pk_bf16_f32 v89, v94, v95
	v_pk_mul_f32 v[84:85], v[84:85], v[98:99] op_sel_hi:[1,0]
	v_cvt_pk_bf16_f32 v90, v90, v91
	v_cvt_pk_bf16_f32 v91, v102, v103
	s_bitcmp1_b32 s100, 0
	s_cbranch_scc0 .Lq_abi_e4
	flat_store_dwordx4 v[100:101], v[88:91]
.Lq_abi_e4:
	v_pk_mul_f32 v[86:87], v[86:87], v[98:99] op_sel_hi:[1,0]
	s_and_b64 vcc, exec, s[38:39]
	v_pk_mul_f32 v[88:89], v[82:83], v[98:99] op_sel_hi:[1,0]
	v_pk_mul_f32 v[82:83], v[80:81], v[98:99] op_sel_hi:[1,0]
	v_cvt_pk_bf16_f32 v80, v84, v85
	v_cvt_pk_bf16_f32 v81, v86, v87
	s_nop 0
	v_cvt_pk_bf16_f32 v82, v82, v83
	v_cvt_pk_bf16_f32 v83, v88, v89
	s_bitcmp1_b32 s100, 1
	s_cbranch_scc0 .Lq_abi_e5
	flat_store_dwordx4 v[100:101], v[80:83] offset:256
.Lq_abi_e5:
	s_nop 1
	v_or_b32_e32 v80, 48, v138
	v_ashrrev_i32_e32 v81, 31, v80
	s_cbranch_vccnz .LBB0_641
	v_lshl_add_u64 v[82:83], v[80:81], 2, s[40:41]
	s_nop 1
	v_mov_b32_e32 v81, v203
	v_fmamk_f32 v81, v81, 0x3a000000, v181
	v_mul_f32_e32 v82, 0x4b800000, v81
	v_cmp_gt_f32_e32 vcc, s80, v81
	s_nop 1
	v_cndmask_b32_e32 v81, v81, v82, vcc
	v_rsq_f32_e32 v81, v81
	s_nop 0
	v_mul_f32_e32 v82, 0x45800000, v81
	v_cndmask_b32_e32 v96, v81, v82, vcc
.LBB0_641:
	v_mov_b64_e32 v[82:83], s[30:31]
	v_mad_i64_i32 v[80:81], s[2:3], v80, s86, v[82:83]
	v_lshl_add_u64 v[80:81], v[140:141], 1, v[80:81]
	v_pk_mul_f32 v[78:79], v[78:79], v[96:97] op_sel_hi:[1,0]
	v_pk_mul_f32 v[76:77], v[76:77], v[96:97] op_sel_hi:[1,0]
	v_pk_mul_f32 v[82:83], v[74:75], v[96:97] op_sel_hi:[1,0]
	v_pk_mul_f32 v[74:75], v[72:73], v[96:97] op_sel_hi:[1,0]
	v_cvt_pk_bf16_f32 v72, v76, v77
	v_cvt_pk_bf16_f32 v73, v78, v79
	v_pk_mul_f32 v[68:69], v[68:69], v[96:97] op_sel_hi:[1,0]
	v_cvt_pk_bf16_f32 v74, v74, v75
	v_cvt_pk_bf16_f32 v75, v82, v83
	s_bitcmp1_b32 s100, 0
	s_cbranch_scc0 .Lq_abi_e6
	flat_store_dwordx4 v[80:81], v[72:75]
.Lq_abi_e6:
	v_pk_mul_f32 v[70:71], v[70:71], v[96:97] op_sel_hi:[1,0]
	s_and_b64 vcc, exec, s[38:39]
	v_pk_mul_f32 v[72:73], v[66:67], v[96:97] op_sel_hi:[1,0]
	v_pk_mul_f32 v[66:67], v[64:65], v[96:97] op_sel_hi:[1,0]
	v_cvt_pk_bf16_f32 v64, v68, v69
	v_cvt_pk_bf16_f32 v65, v70, v71
	v_add_u32_e32 v68, 0x80, v138
	v_cvt_pk_bf16_f32 v66, v66, v67
	v_cvt_pk_bf16_f32 v67, v72, v73
	s_bitcmp1_b32 s100, 1
	s_cbranch_scc0 .Lq_abi_e7
	flat_store_dwordx4 v[80:81], v[64:67] offset:256
.Lq_abi_e7:
	v_ashrrev_i32_e32 v69, 31, v68
	s_nop 0
	v_mov_b32_e32 v64, 1.0
	v_mov_b32_e32 v66, 1.0
	s_cbranch_vccnz .LBB0_643
	v_lshl_add_u64 v[66:67], v[68:69], 2, s[40:41]
	s_nop 1
	v_mov_b32_e32 v65, v204
	v_fmamk_f32 v65, v65, 0x3a000000, v181
	v_mul_f32_e32 v66, 0x4b800000, v65
	v_cmp_gt_f32_e32 vcc, s80, v65
	s_nop 1
	v_cndmask_b32_e32 v65, v65, v66, vcc
	v_rsq_f32_e32 v65, v65
	s_nop 0
	v_mul_f32_e32 v66, 0x45800000, v65
	v_cndmask_b32_e32 v66, v65, v66, vcc
.LBB0_643:
	v_mov_b64_e32 v[70:71], s[30:31]
	v_mad_i64_i32 v[68:69], s[2:3], v68, s86, v[70:71]
	v_lshl_add_u64 v[68:69], v[140:141], 1, v[68:69]
	v_pk_mul_f32 v[62:63], v[62:63], v[66:67] op_sel_hi:[1,0]
	v_pk_mul_f32 v[60:61], v[60:61], v[66:67] op_sel_hi:[1,0]
	v_pk_mul_f32 v[70:71], v[58:59], v[66:67] op_sel_hi:[1,0]
	v_pk_mul_f32 v[58:59], v[56:57], v[66:67] op_sel_hi:[1,0]
	v_cvt_pk_bf16_f32 v56, v60, v61
	v_cvt_pk_bf16_f32 v57, v62, v63
	v_pk_mul_f32 v[52:53], v[52:53], v[66:67] op_sel_hi:[1,0]
	v_cvt_pk_bf16_f32 v58, v58, v59
	v_cvt_pk_bf16_f32 v59, v70, v71
	s_bitcmp1_b32 s100, 2
	s_cbranch_scc0 .Lq_abi_e8
	flat_store_dwordx4 v[68:69], v[56:59]
.Lq_abi_e8:
	v_pk_mul_f32 v[54:55], v[54:55], v[66:67] op_sel_hi:[1,0]
	s_and_b64 vcc, exec, s[38:39]
	v_pk_mul_f32 v[56:57], v[50:51], v[66:67] op_sel_hi:[1,0]
	v_pk_mul_f32 v[50:51], v[48:49], v[66:67] op_sel_hi:[1,0]
	v_cvt_pk_bf16_f32 v48, v52, v53
	v_cvt_pk_bf16_f32 v49, v54, v55
	s_nop 0
	v_cvt_pk_bf16_f32 v50, v50, v51
	v_cvt_pk_bf16_f32 v51, v56, v57
	s_bitcmp1_b32 s100, 3
	s_cbranch_scc0 .Lq_abi_e9
	flat_store_dwordx4 v[68:69], v[48:51] offset:256
.Lq_abi_e9:
	s_nop 1
	v_add_u32_e32 v48, 0x90, v138
	v_ashrrev_i32_e32 v49, 31, v48
	s_cbranch_vccnz .LBB0_645
	v_lshl_add_u64 v[50:51], v[48:49], 2, s[40:41]
	s_nop 1
	v_mov_b32_e32 v49, v205
	v_fmamk_f32 v49, v49, 0x3a000000, v181
	v_mul_f32_e32 v50, 0x4b800000, v49
	v_cmp_gt_f32_e32 vcc, s80, v49
	s_nop 1
	v_cndmask_b32_e32 v49, v49, v50, vcc
	v_rsq_f32_e32 v49, v49
	s_nop 0
	v_mul_f32_e32 v50, 0x45800000, v49
	v_cndmask_b32_e32 v64, v49, v50, vcc
.LBB0_645:
	v_mov_b64_e32 v[50:51], s[30:31]
	v_mad_i64_i32 v[48:49], s[2:3], v48, s86, v[50:51]
	v_lshl_add_u64 v[48:49], v[140:141], 1, v[48:49]
	v_pk_mul_f32 v[46:47], v[46:47], v[64:65] op_sel_hi:[1,0]
	v_pk_mul_f32 v[44:45], v[44:45], v[64:65] op_sel_hi:[1,0]
	v_pk_mul_f32 v[50:51], v[42:43], v[64:65] op_sel_hi:[1,0]
	v_pk_mul_f32 v[42:43], v[40:41], v[64:65] op_sel_hi:[1,0]
	v_cvt_pk_bf16_f32 v40, v44, v45
	v_cvt_pk_bf16_f32 v41, v46, v47
	v_pk_mul_f32 v[36:37], v[36:37], v[64:65] op_sel_hi:[1,0]
	v_cvt_pk_bf16_f32 v42, v42, v43
	v_cvt_pk_bf16_f32 v43, v50, v51
	s_bitcmp1_b32 s100, 2
	s_cbranch_scc0 .Lq_abi_e10
	flat_store_dwordx4 v[48:49], v[40:43]
.Lq_abi_e10:
	v_pk_mul_f32 v[38:39], v[38:39], v[64:65] op_sel_hi:[1,0]
	s_and_b64 vcc, exec, s[38:39]
	v_pk_mul_f32 v[40:41], v[34:35], v[64:65] op_sel_hi:[1,0]
	v_pk_mul_f32 v[34:35], v[32:33], v[64:65] op_sel_hi:[1,0]
	v_cvt_pk_bf16_f32 v32, v36, v37
	v_cvt_pk_bf16_f32 v33, v38, v39
	v_add_u32_e32 v36, 0xa0, v138
	v_cvt_pk_bf16_f32 v34, v34, v35
	v_cvt_pk_bf16_f32 v35, v40, v41
	s_bitcmp1_b32 s100, 3
	s_cbranch_scc0 .Lq_abi_e11
	flat_store_dwordx4 v[48:49], v[32:35] offset:256
.Lq_abi_e11:
	v_ashrrev_i32_e32 v37, 31, v36
	s_nop 0
	v_mov_b32_e32 v32, 1.0
	v_mov_b32_e32 v34, 1.0
	s_cbranch_vccnz .LBB0_647
	v_lshl_add_u64 v[34:35], v[36:37], 2, s[40:41]
	s_nop 1
	v_mov_b32_e32 v33, v206
	v_fmamk_f32 v33, v33, 0x3a000000, v181
	v_mul_f32_e32 v34, 0x4b800000, v33
	v_cmp_gt_f32_e32 vcc, s80, v33
	s_nop 1
	v_cndmask_b32_e32 v33, v33, v34, vcc
	v_rsq_f32_e32 v33, v33
	s_nop 0
	v_mul_f32_e32 v34, 0x45800000, v33
	v_cndmask_b32_e32 v34, v33, v34, vcc
.LBB0_647:
	v_mov_b64_e32 v[38:39], s[30:31]
	v_mad_i64_i32 v[36:37], s[2:3], v36, s86, v[38:39]
	v_lshl_add_u64 v[36:37], v[140:141], 1, v[36:37]
	v_pk_mul_f32 v[30:31], v[30:31], v[34:35] op_sel_hi:[1,0]
	v_pk_mul_f32 v[28:29], v[28:29], v[34:35] op_sel_hi:[1,0]
	v_pk_mul_f32 v[38:39], v[26:27], v[34:35] op_sel_hi:[1,0]
	v_pk_mul_f32 v[26:27], v[24:25], v[34:35] op_sel_hi:[1,0]
	v_cvt_pk_bf16_f32 v24, v28, v29
	v_cvt_pk_bf16_f32 v25, v30, v31
	v_pk_mul_f32 v[20:21], v[20:21], v[34:35] op_sel_hi:[1,0]
	v_cvt_pk_bf16_f32 v26, v26, v27
	v_cvt_pk_bf16_f32 v27, v38, v39
	s_bitcmp1_b32 s100, 2
	s_cbranch_scc0 .Lq_abi_e12
	flat_store_dwordx4 v[36:37], v[24:27]
.Lq_abi_e12:
	v_pk_mul_f32 v[22:23], v[22:23], v[34:35] op_sel_hi:[1,0]
	s_and_b64 vcc, exec, s[38:39]
	v_pk_mul_f32 v[24:25], v[18:19], v[34:35] op_sel_hi:[1,0]
	v_pk_mul_f32 v[18:19], v[16:17], v[34:35] op_sel_hi:[1,0]
	v_cvt_pk_bf16_f32 v16, v20, v21
	v_cvt_pk_bf16_f32 v17, v22, v23
	s_nop 0
	v_cvt_pk_bf16_f32 v18, v18, v19
	v_cvt_pk_bf16_f32 v19, v24, v25
	s_bitcmp1_b32 s100, 3
	s_cbranch_scc0 .Lq_abi_e13
	flat_store_dwordx4 v[36:37], v[16:19] offset:256
.Lq_abi_e13:
	s_nop 1
	v_add_u32_e32 v16, 0xb0, v138
	v_ashrrev_i32_e32 v17, 31, v16
	s_cbranch_vccnz .LBB0_649
	v_lshl_add_u64 v[18:19], v[16:17], 2, s[40:41]
	s_nop 1
	v_mov_b32_e32 v17, v207
	v_fmamk_f32 v17, v17, 0x3a000000, v181
	v_mul_f32_e32 v18, 0x4b800000, v17
	v_cmp_gt_f32_e32 vcc, s80, v17
	s_nop 1
	v_cndmask_b32_e32 v17, v17, v18, vcc
	v_rsq_f32_e32 v17, v17
	s_nop 0
	v_mul_f32_e32 v18, 0x45800000, v17
	v_cndmask_b32_e32 v32, v17, v18, vcc
.LBB0_649:
	v_mov_b64_e32 v[18:19], s[30:31]
	v_mad_i64_i32 v[16:17], s[2:3], v16, s86, v[18:19]
	v_lshl_add_u64 v[16:17], v[140:141], 1, v[16:17]
	v_pk_mul_f32 v[14:15], v[14:15], v[32:33] op_sel_hi:[1,0]
	v_pk_mul_f32 v[12:13], v[12:13], v[32:33] op_sel_hi:[1,0]
	v_pk_mul_f32 v[18:19], v[10:11], v[32:33] op_sel_hi:[1,0]
	v_pk_mul_f32 v[10:11], v[8:9], v[32:33] op_sel_hi:[1,0]
	v_cvt_pk_bf16_f32 v8, v12, v13
	v_cvt_pk_bf16_f32 v9, v14, v15
	s_andn2_b64 vcc, exec, s[36:37]
	v_cvt_pk_bf16_f32 v10, v10, v11
	v_cvt_pk_bf16_f32 v11, v18, v19
	s_bitcmp1_b32 s100, 2
	s_cbranch_scc0 .Lq_abi_e14
	flat_store_dwordx4 v[16:17], v[8:11]
.Lq_abi_e14:
	s_mov_b64 s[2:3], -1
	v_pk_mul_f32 v[6:7], v[6:7], v[32:33] op_sel_hi:[1,0]
	v_pk_mul_f32 v[8:9], v[2:3], v[32:33] op_sel_hi:[1,0]
	v_pk_mul_f32 v[2:3], v[0:1], v[32:33] op_sel_hi:[1,0]
	v_pk_mul_f32 v[4:5], v[4:5], v[32:33] op_sel_hi:[1,0]
	s_nop 0
	v_cvt_pk_bf16_f32 v0, v4, v5
	v_cvt_pk_bf16_f32 v1, v6, v7
	v_cvt_pk_bf16_f32 v2, v2, v3
	v_cvt_pk_bf16_f32 v3, v8, v9
	s_bitcmp1_b32 s100, 3
	s_cbranch_scc0 .Lq_abi_e15
	flat_store_dwordx4 v[16:17], v[0:3] offset:256
.Lq_abi_e15:
	s_cbranch_vccnz .LBB0_622
	s_andn2_b64 vcc, exec, s[28:29]
	s_cbranch_vccnz .LBB0_621
	s_barrier
	s_branch .LBB0_621
